# conformer part: depthwise-conv input-row LDS reads issued 3 rows ahead (ring of 4 registers, one base + immediate offsets)
# speedup vs baseline: 1.0356x; 1.0014x over previous
.LBB0_593:
	s_or_b64 exec, exec, s[26:27]
	s_ashr_i32 s27, s66, 6
	s_lshl_b32 s26, s27, 5
	v_and_b32_e32 v158, 15, v156
	s_add_i32 s23, s26, s24
	v_or_b32_e32 v0, s23, v158
	v_ashrrev_i32_e32 v1, 31, v0
	v_readlane_b32 s42, v254, 56
	v_lshlrev_b64 v[0:1], 9, v[0:1]
	v_readlane_b32 s43, v254, 57
	v_and_b32_e32 v148, 48, v156
	v_ashrrev_i32_e32 v166, 3, v156
	v_lshl_add_u64 v[0:1], s[42:43], 0, v[0:1]
	v_lshl_add_u64 v[0:1], v[0:1], 0, v[148:149]
	v_and_b32_e32 v159, -16, v166
	v_lshl_add_u32 v167, v157, 2, 0
	v_add_co_u32_e32 v2, vcc, 0x2000, v0
	v_lshl_add_u32 v161, v159, 9, v167
	s_nop 0
	v_addc_co_u32_e32 v3, vcc, 0, v1, vcc
	global_load_dwordx4 v[56:59], v[0:1], off
	global_load_dwordx4 v[48:51], v[0:1], off offset:64
	global_load_dwordx4 v[60:63], v[2:3], off
	global_load_dwordx4 v[52:55], v[2:3], off offset:64
	global_load_dwordx4 v[40:43], v[0:1], off offset:128
	global_load_dwordx4 v[32:35], v[0:1], off offset:192
	global_load_dwordx4 v[44:47], v[2:3], off offset:128
	global_load_dwordx4 v[36:39], v[2:3], off offset:192
	global_load_dwordx4 v[24:27], v[0:1], off offset:256
	global_load_dwordx4 v[16:19], v[0:1], off offset:320
	global_load_dwordx4 v[28:31], v[2:3], off offset:256
	global_load_dwordx4 v[20:23], v[2:3], off offset:320
	v_mov_b32_e32 v248, v161
	ds_read_b32 v244, v248
	ds_read_b32 v245, v248 offset:512
	ds_read_b32 v246, v248 offset:1024
	ds_read_b32 v247, v248 offset:1536
	v_or_b32_e32 v160, 1, v159
	v_mov_b64_e32 v[164:165], v[126:127]
	v_mov_b64_e32 v[168:169], v[126:127]
	v_mov_b64_e32 v[170:171], v[126:127]
	s_waitcnt lgkmcnt(3)
	v_mov_b32_e32 v129, v244
	v_lshlrev_b32_e32 v128, 16, v129
	v_and_b32_e32 v129, 0xffff0000, v129
	v_pk_fma_f32 v[162:163], v[124:125], v[128:129], v[126:127]
	v_mov_b64_e32 v[172:173], v[126:127]
	v_mov_b64_e32 v[174:175], v[126:127]
	v_mov_b64_e32 v[144:145], v[126:127]
	v_mov_b64_e32 v[142:143], v[126:127]
	v_mov_b64_e32 v[140:141], v[126:127]
	v_mov_b64_e32 v[138:139], v[126:127]
	v_mov_b64_e32 v[136:137], v[126:127]
	v_mov_b64_e32 v[134:135], v[126:127]
	v_mov_b64_e32 v[132:133], v[126:127]
	v_mov_b64_e32 v[130:131], v[126:127]
	v_mov_b64_e32 v[128:129], v[126:127]
	v_lshl_add_u32 v154, v160, 9, v167
	global_load_dwordx4 v[8:11], v[0:1], off offset:384
	global_load_dwordx4 v[4:7], v[0:1], off offset:448
	global_load_dwordx4 v[12:15], v[2:3], off offset:384
	s_nop 0
	global_load_dwordx4 v[0:3], v[2:3], off offset:448
	ds_read_b32 v244, v248 offset:2048
	v_readlane_b32 s42, v255, 5
	v_readlane_b32 s43, v255, 6
	s_lshl_b32 s23, s27, 13
	s_add_i32 s23, s23, 0
	s_waitcnt lgkmcnt(3)
	v_mov_b32_e32 v154, v245
	v_lshlrev_b32_e32 v176, 16, v154
	v_and_b32_e32 v177, 0xffff0000, v154
	v_pk_fma_f32 v[162:163], v[122:123], v[176:177], v[162:163]
	v_pk_fma_f32 v[176:177], v[124:125], v[176:177], v[126:127]
	v_or_b32_e32 v126, 2, v159
	v_lshl_add_u32 v127, v126, 9, v167
	ds_read_b32 v245, v248 offset:2560
	s_mov_b32 s46, 0x3b800000
	s_waitcnt lgkmcnt(3)
	v_mov_b32_e32 v127, v246
	v_lshlrev_b32_e32 v178, 16, v127
	v_and_b32_e32 v179, 0xffff0000, v127
	v_or_b32_e32 v127, 3, v159
	v_pk_fma_f32 v[162:163], v[120:121], v[178:179], v[162:163]
	v_pk_fma_f32 v[176:177], v[122:123], v[178:179], v[176:177]
	v_pk_fma_f32 v[164:165], v[124:125], v[178:179], v[164:165]
	v_lshl_add_u32 v154, v127, 9, v167
	ds_read_b32 v246, v248 offset:3072
	s_waitcnt lgkmcnt(3)
	v_mov_b32_e32 v154, v247
	v_lshlrev_b32_e32 v178, 16, v154
	v_and_b32_e32 v179, 0xffff0000, v154
	v_pk_fma_f32 v[180:181], v[118:119], v[178:179], v[162:163]
	v_or_b32_e32 v162, 4, v159
	v_pk_fma_f32 v[176:177], v[120:121], v[178:179], v[176:177]
	v_pk_fma_f32 v[164:165], v[122:123], v[178:179], v[164:165]
	v_pk_fma_f32 v[168:169], v[124:125], v[178:179], v[168:169]
	v_lshl_add_u32 v154, v162, 9, v167
	ds_read_b32 v247, v248 offset:3584
	v_or_b32_e32 v163, 5, v159
	s_waitcnt lgkmcnt(3)
	v_mov_b32_e32 v154, v244
	v_lshlrev_b32_e32 v178, 16, v154
	v_and_b32_e32 v179, 0xffff0000, v154
	v_pk_fma_f32 v[180:181], v[116:117], v[178:179], v[180:181]
	v_pk_fma_f32 v[176:177], v[118:119], v[178:179], v[176:177]
	v_pk_fma_f32 v[164:165], v[120:121], v[178:179], v[164:165]
	v_pk_fma_f32 v[168:169], v[122:123], v[178:179], v[168:169]
	v_pk_fma_f32 v[170:171], v[124:125], v[178:179], v[170:171]
	v_lshl_add_u32 v154, v163, 9, v167
	ds_read_b32 v244, v248 offset:4096
	s_waitcnt lgkmcnt(3)
	v_mov_b32_e32 v154, v245
	v_lshlrev_b32_e32 v178, 16, v154
	v_and_b32_e32 v179, 0xffff0000, v154
	v_pk_fma_f32 v[182:183], v[118:119], v[178:179], v[164:165]
	v_or_b32_e32 v164, 6, v159
	v_pk_fma_f32 v[180:181], v[114:115], v[178:179], v[180:181]
	v_pk_fma_f32 v[176:177], v[116:117], v[178:179], v[176:177]
	v_pk_fma_f32 v[168:169], v[120:121], v[178:179], v[168:169]
	v_pk_fma_f32 v[170:171], v[122:123], v[178:179], v[170:171]
	v_pk_fma_f32 v[172:173], v[124:125], v[178:179], v[172:173]
	v_lshl_add_u32 v154, v164, 9, v167
	ds_read_b32 v245, v248 offset:4608
	v_or_b32_e32 v165, 7, v159
	s_waitcnt lgkmcnt(3)
	v_mov_b32_e32 v154, v246
	v_lshlrev_b32_e32 v178, 16, v154
	v_and_b32_e32 v179, 0xffff0000, v154
	v_pk_fma_f32 v[180:181], v[112:113], v[178:179], v[180:181]
	v_pk_fma_f32 v[176:177], v[114:115], v[178:179], v[176:177]
	v_pk_fma_f32 v[182:183], v[116:117], v[178:179], v[182:183]
	v_pk_fma_f32 v[168:169], v[118:119], v[178:179], v[168:169]
	v_pk_fma_f32 v[170:171], v[120:121], v[178:179], v[170:171]
	v_pk_fma_f32 v[172:173], v[122:123], v[178:179], v[172:173]
	v_pk_fma_f32 v[174:175], v[124:125], v[178:179], v[174:175]
	v_lshl_add_u32 v154, v165, 9, v167
	ds_read_b32 v246, v248 offset:5120
	s_waitcnt lgkmcnt(3)
	v_mov_b32_e32 v154, v247
	v_lshlrev_b32_e32 v178, 16, v154
	v_and_b32_e32 v179, 0xffff0000, v154
	v_pk_fma_f32 v[180:181], v[110:111], v[178:179], v[180:181]
	v_pk_fma_f32 v[176:177], v[112:113], v[178:179], v[176:177]
	v_pk_fma_f32 v[182:183], v[114:115], v[178:179], v[182:183]
	v_pk_fma_f32 v[168:169], v[116:117], v[178:179], v[168:169]
	v_pk_fma_f32 v[170:171], v[118:119], v[178:179], v[170:171]
	v_pk_fma_f32 v[172:173], v[120:121], v[178:179], v[172:173]
	v_pk_fma_f32 v[174:175], v[122:123], v[178:179], v[174:175]
	v_pk_fma_f32 v[178:179], v[124:125], v[178:179], v[144:145]
	v_or_b32_e32 v144, 8, v159
	v_lshl_add_u32 v145, v144, 9, v167
	ds_read_b32 v247, v248 offset:5632
	s_waitcnt lgkmcnt(3)
	v_mov_b32_e32 v145, v244
	v_lshlrev_b32_e32 v184, 16, v145
	v_and_b32_e32 v185, 0xffff0000, v145
	v_pk_fma_f32 v[180:181], v[108:109], v[184:185], v[180:181]
	v_pk_fma_f32 v[176:177], v[110:111], v[184:185], v[176:177]
	v_pk_fma_f32 v[182:183], v[112:113], v[184:185], v[182:183]
	v_pk_fma_f32 v[168:169], v[114:115], v[184:185], v[168:169]
	v_pk_fma_f32 v[170:171], v[116:117], v[184:185], v[170:171]
	v_pk_fma_f32 v[172:173], v[118:119], v[184:185], v[172:173]
	v_pk_fma_f32 v[174:175], v[120:121], v[184:185], v[174:175]
	v_pk_fma_f32 v[178:179], v[122:123], v[184:185], v[178:179]
	v_pk_fma_f32 v[184:185], v[124:125], v[184:185], v[142:143]
	v_or_b32_e32 v142, 9, v159
	v_lshl_add_u32 v143, v142, 9, v167
	ds_read_b32 v244, v248 offset:6144
	s_waitcnt lgkmcnt(3)
	v_mov_b32_e32 v143, v245
	v_lshlrev_b32_e32 v186, 16, v143
	v_and_b32_e32 v187, 0xffff0000, v143
	v_pk_fma_f32 v[180:181], v[106:107], v[186:187], v[180:181]
	v_pk_fma_f32 v[176:177], v[108:109], v[186:187], v[176:177]
	v_pk_fma_f32 v[182:183], v[110:111], v[186:187], v[182:183]
	v_pk_fma_f32 v[168:169], v[112:113], v[186:187], v[168:169]
	v_pk_fma_f32 v[170:171], v[114:115], v[186:187], v[170:171]
	v_pk_fma_f32 v[172:173], v[116:117], v[186:187], v[172:173]
	v_pk_fma_f32 v[174:175], v[118:119], v[186:187], v[174:175]
	v_pk_fma_f32 v[178:179], v[120:121], v[186:187], v[178:179]
	v_pk_fma_f32 v[184:185], v[122:123], v[186:187], v[184:185]
	v_pk_fma_f32 v[186:187], v[124:125], v[186:187], v[140:141]
	v_or_b32_e32 v140, 10, v159
	v_lshl_add_u32 v141, v140, 9, v167
	ds_read_b32 v245, v248 offset:6656
	s_waitcnt lgkmcnt(3)
	v_mov_b32_e32 v141, v246
	v_lshlrev_b32_e32 v188, 16, v141
	v_and_b32_e32 v189, 0xffff0000, v141
	v_pk_fma_f32 v[180:181], v[104:105], v[188:189], v[180:181]
	v_pk_fma_f32 v[176:177], v[106:107], v[188:189], v[176:177]
	v_pk_fma_f32 v[182:183], v[108:109], v[188:189], v[182:183]
	v_pk_fma_f32 v[168:169], v[110:111], v[188:189], v[168:169]
	v_pk_fma_f32 v[170:171], v[112:113], v[188:189], v[170:171]
	v_pk_fma_f32 v[172:173], v[114:115], v[188:189], v[172:173]
	v_pk_fma_f32 v[174:175], v[116:117], v[188:189], v[174:175]
	v_pk_fma_f32 v[178:179], v[118:119], v[188:189], v[178:179]
	v_pk_fma_f32 v[184:185], v[120:121], v[188:189], v[184:185]
	v_pk_fma_f32 v[186:187], v[122:123], v[188:189], v[186:187]
	v_pk_fma_f32 v[188:189], v[124:125], v[188:189], v[138:139]
	v_or_b32_e32 v138, 11, v159
	v_lshl_add_u32 v139, v138, 9, v167
	ds_read_b32 v246, v248 offset:7168
	s_waitcnt lgkmcnt(3)
	v_mov_b32_e32 v139, v247
	v_lshlrev_b32_e32 v190, 16, v139
	v_and_b32_e32 v191, 0xffff0000, v139
	v_pk_fma_f32 v[180:181], v[102:103], v[190:191], v[180:181]
	v_pk_fma_f32 v[176:177], v[104:105], v[190:191], v[176:177]
	v_pk_fma_f32 v[182:183], v[106:107], v[190:191], v[182:183]
	v_pk_fma_f32 v[168:169], v[108:109], v[190:191], v[168:169]
	v_pk_fma_f32 v[170:171], v[110:111], v[190:191], v[170:171]
	v_pk_fma_f32 v[172:173], v[112:113], v[190:191], v[172:173]
	v_pk_fma_f32 v[174:175], v[114:115], v[190:191], v[174:175]
	v_pk_fma_f32 v[178:179], v[116:117], v[190:191], v[178:179]
	v_pk_fma_f32 v[184:185], v[118:119], v[190:191], v[184:185]
	v_pk_fma_f32 v[186:187], v[120:121], v[190:191], v[186:187]
	v_pk_fma_f32 v[188:189], v[122:123], v[190:191], v[188:189]
	v_pk_fma_f32 v[190:191], v[124:125], v[190:191], v[136:137]
	v_or_b32_e32 v136, 12, v159
	v_lshl_add_u32 v137, v136, 9, v167
	ds_read_b32 v247, v248 offset:7680
	s_waitcnt lgkmcnt(3)
	v_mov_b32_e32 v137, v244
	v_lshlrev_b32_e32 v192, 16, v137
	v_and_b32_e32 v193, 0xffff0000, v137
	v_pk_fma_f32 v[180:181], v[100:101], v[192:193], v[180:181]
	v_pk_fma_f32 v[176:177], v[102:103], v[192:193], v[176:177]
	v_pk_fma_f32 v[182:183], v[104:105], v[192:193], v[182:183]
	v_pk_fma_f32 v[168:169], v[106:107], v[192:193], v[168:169]
	v_pk_fma_f32 v[170:171], v[108:109], v[192:193], v[170:171]
	v_pk_fma_f32 v[172:173], v[110:111], v[192:193], v[172:173]
	v_pk_fma_f32 v[174:175], v[112:113], v[192:193], v[174:175]
	v_pk_fma_f32 v[178:179], v[114:115], v[192:193], v[178:179]
	v_pk_fma_f32 v[184:185], v[116:117], v[192:193], v[184:185]
	v_pk_fma_f32 v[186:187], v[118:119], v[192:193], v[186:187]
	v_pk_fma_f32 v[188:189], v[120:121], v[192:193], v[188:189]
	v_pk_fma_f32 v[190:191], v[122:123], v[192:193], v[190:191]
	v_pk_fma_f32 v[192:193], v[124:125], v[192:193], v[134:135]
	v_or_b32_e32 v134, 13, v159
	v_lshl_add_u32 v135, v134, 9, v167
	ds_read_b32 v244, v248 offset:8192
	s_waitcnt lgkmcnt(3)
	v_mov_b32_e32 v135, v245
	v_lshlrev_b32_e32 v194, 16, v135
	v_and_b32_e32 v195, 0xffff0000, v135
	v_pk_fma_f32 v[180:181], v[98:99], v[194:195], v[180:181]
	v_pk_fma_f32 v[176:177], v[100:101], v[194:195], v[176:177]
	v_pk_fma_f32 v[182:183], v[102:103], v[194:195], v[182:183]
	v_pk_fma_f32 v[168:169], v[104:105], v[194:195], v[168:169]
	v_pk_fma_f32 v[170:171], v[106:107], v[194:195], v[170:171]
	v_pk_fma_f32 v[172:173], v[108:109], v[194:195], v[172:173]
	v_pk_fma_f32 v[174:175], v[110:111], v[194:195], v[174:175]
	v_pk_fma_f32 v[178:179], v[112:113], v[194:195], v[178:179]
	v_pk_fma_f32 v[184:185], v[114:115], v[194:195], v[184:185]
	v_pk_fma_f32 v[186:187], v[116:117], v[194:195], v[186:187]
	v_pk_fma_f32 v[188:189], v[118:119], v[194:195], v[188:189]
	v_pk_fma_f32 v[190:191], v[120:121], v[194:195], v[190:191]
	v_pk_fma_f32 v[192:193], v[122:123], v[194:195], v[192:193]
	v_pk_fma_f32 v[194:195], v[124:125], v[194:195], v[132:133]
	v_or_b32_e32 v132, 14, v159
	v_lshl_add_u32 v133, v132, 9, v167
	ds_read_b32 v245, v248 offset:8704
	s_waitcnt lgkmcnt(3)
	v_mov_b32_e32 v133, v246
	v_lshlrev_b32_e32 v196, 16, v133
	v_and_b32_e32 v197, 0xffff0000, v133
	v_pk_fma_f32 v[180:181], v[96:97], v[196:197], v[180:181]
	v_pk_fma_f32 v[176:177], v[98:99], v[196:197], v[176:177]
	v_pk_fma_f32 v[182:183], v[100:101], v[196:197], v[182:183]
	v_pk_fma_f32 v[168:169], v[102:103], v[196:197], v[168:169]
	v_pk_fma_f32 v[170:171], v[104:105], v[196:197], v[170:171]
	v_pk_fma_f32 v[172:173], v[106:107], v[196:197], v[172:173]
	v_pk_fma_f32 v[174:175], v[108:109], v[196:197], v[174:175]
	v_pk_fma_f32 v[178:179], v[110:111], v[196:197], v[178:179]
	v_pk_fma_f32 v[184:185], v[112:113], v[196:197], v[184:185]
	v_pk_fma_f32 v[186:187], v[114:115], v[196:197], v[186:187]
	v_pk_fma_f32 v[188:189], v[116:117], v[196:197], v[188:189]
	v_pk_fma_f32 v[190:191], v[118:119], v[196:197], v[190:191]
	v_pk_fma_f32 v[192:193], v[120:121], v[196:197], v[192:193]
	v_pk_fma_f32 v[194:195], v[122:123], v[196:197], v[194:195]
	v_pk_fma_f32 v[196:197], v[124:125], v[196:197], v[130:131]
	v_or_b32_e32 v130, 15, v166
	v_lshl_add_u32 v131, v130, 9, v167
	ds_read_b32 v246, v248 offset:9216
	s_waitcnt lgkmcnt(3)
	v_mov_b32_e32 v131, v247
	v_lshlrev_b32_e32 v166, 16, v131
	v_and_b32_e32 v167, 0xffff0000, v131
	v_pk_fma_f32 v[180:181], v[94:95], v[166:167], v[180:181]
	v_pk_fma_f32 v[176:177], v[96:97], v[166:167], v[176:177]
	v_pk_fma_f32 v[182:183], v[98:99], v[166:167], v[182:183]
	v_pk_fma_f32 v[168:169], v[100:101], v[166:167], v[168:169]
	v_pk_fma_f32 v[170:171], v[102:103], v[166:167], v[170:171]
	v_pk_fma_f32 v[172:173], v[104:105], v[166:167], v[172:173]
	v_pk_fma_f32 v[174:175], v[106:107], v[166:167], v[174:175]
	v_pk_fma_f32 v[178:179], v[108:109], v[166:167], v[178:179]
	v_pk_fma_f32 v[184:185], v[110:111], v[166:167], v[184:185]
	v_pk_fma_f32 v[186:187], v[112:113], v[166:167], v[186:187]
	v_pk_fma_f32 v[188:189], v[114:115], v[166:167], v[188:189]
	v_pk_fma_f32 v[190:191], v[116:117], v[166:167], v[190:191]
	v_pk_fma_f32 v[192:193], v[118:119], v[166:167], v[192:193]
	v_pk_fma_f32 v[194:195], v[120:121], v[166:167], v[194:195]
	v_pk_fma_f32 v[196:197], v[122:123], v[166:167], v[196:197]
	v_pk_fma_f32 v[124:125], v[124:125], v[166:167], v[128:129]
	s_nop 0
	ds_read_b32 v247, v248 offset:9728
	s_waitcnt lgkmcnt(3)
	v_mov_b32_e32 v129, v244
	v_lshlrev_b32_e32 v128, 16, v129
	v_and_b32_e32 v129, 0xffff0000, v129
	v_pk_fma_f32 v[166:167], v[92:93], v[128:129], v[180:181]
	v_pk_fma_f32 v[176:177], v[94:95], v[128:129], v[176:177]
	v_pk_fma_f32 v[180:181], v[96:97], v[128:129], v[182:183]
	v_pk_fma_f32 v[168:169], v[98:99], v[128:129], v[168:169]
	v_pk_fma_f32 v[170:171], v[100:101], v[128:129], v[170:171]
	v_pk_fma_f32 v[172:173], v[102:103], v[128:129], v[172:173]
	v_pk_fma_f32 v[174:175], v[104:105], v[128:129], v[174:175]
	v_pk_fma_f32 v[178:179], v[106:107], v[128:129], v[178:179]
	v_pk_fma_f32 v[182:183], v[108:109], v[128:129], v[184:185]
	v_pk_fma_f32 v[184:185], v[110:111], v[128:129], v[186:187]
	v_pk_fma_f32 v[186:187], v[112:113], v[128:129], v[188:189]
	v_pk_fma_f32 v[188:189], v[114:115], v[128:129], v[190:191]
	v_pk_fma_f32 v[190:191], v[116:117], v[128:129], v[192:193]
	v_pk_fma_f32 v[192:193], v[118:119], v[128:129], v[194:195]
	v_pk_fma_f32 v[194:195], v[120:121], v[128:129], v[196:197]
	v_pk_fma_f32 v[122:123], v[122:123], v[128:129], v[124:125]
	s_nop 0
	ds_read_b32 v244, v248 offset:10240
	s_waitcnt lgkmcnt(3)
	v_mov_b32_e32 v125, v245
	v_lshlrev_b32_e32 v124, 16, v125
	v_and_b32_e32 v125, 0xffff0000, v125
	v_pk_fma_f32 v[128:129], v[90:91], v[124:125], v[166:167]
	v_pk_fma_f32 v[166:167], v[92:93], v[124:125], v[176:177]
	v_pk_fma_f32 v[176:177], v[94:95], v[124:125], v[180:181]
	v_pk_fma_f32 v[168:169], v[96:97], v[124:125], v[168:169]
	v_pk_fma_f32 v[170:171], v[98:99], v[124:125], v[170:171]
	v_pk_fma_f32 v[172:173], v[100:101], v[124:125], v[172:173]
	v_pk_fma_f32 v[174:175], v[102:103], v[124:125], v[174:175]
	v_pk_fma_f32 v[178:179], v[104:105], v[124:125], v[178:179]
	v_pk_fma_f32 v[180:181], v[106:107], v[124:125], v[182:183]
	v_pk_fma_f32 v[182:183], v[108:109], v[124:125], v[184:185]
	v_pk_fma_f32 v[184:185], v[110:111], v[124:125], v[186:187]
	v_pk_fma_f32 v[186:187], v[112:113], v[124:125], v[188:189]
	v_pk_fma_f32 v[188:189], v[114:115], v[124:125], v[190:191]
	v_pk_fma_f32 v[190:191], v[116:117], v[124:125], v[192:193]
	v_pk_fma_f32 v[192:193], v[118:119], v[124:125], v[194:195]
	v_pk_fma_f32 v[120:121], v[120:121], v[124:125], v[122:123]
	s_nop 0
	ds_read_b32 v245, v248 offset:10752
	s_waitcnt lgkmcnt(3)
	v_mov_b32_e32 v123, v246
	v_lshlrev_b32_e32 v122, 16, v123
	v_and_b32_e32 v123, 0xffff0000, v123
	v_pk_fma_f32 v[124:125], v[88:89], v[122:123], v[128:129]
	v_pk_fma_f32 v[128:129], v[90:91], v[122:123], v[166:167]
	v_pk_fma_f32 v[166:167], v[92:93], v[122:123], v[176:177]
	v_pk_fma_f32 v[168:169], v[94:95], v[122:123], v[168:169]
	v_pk_fma_f32 v[170:171], v[96:97], v[122:123], v[170:171]
	v_pk_fma_f32 v[172:173], v[98:99], v[122:123], v[172:173]
	v_pk_fma_f32 v[174:175], v[100:101], v[122:123], v[174:175]
	v_pk_fma_f32 v[176:177], v[102:103], v[122:123], v[178:179]
	v_pk_fma_f32 v[178:179], v[104:105], v[122:123], v[180:181]
	v_pk_fma_f32 v[180:181], v[106:107], v[122:123], v[182:183]
	v_pk_fma_f32 v[182:183], v[108:109], v[122:123], v[184:185]
	v_pk_fma_f32 v[184:185], v[110:111], v[122:123], v[186:187]
	v_pk_fma_f32 v[186:187], v[112:113], v[122:123], v[188:189]
	v_pk_fma_f32 v[188:189], v[114:115], v[122:123], v[190:191]
	v_pk_fma_f32 v[190:191], v[116:117], v[122:123], v[192:193]
	v_pk_fma_f32 v[118:119], v[118:119], v[122:123], v[120:121]
	s_nop 0
	ds_read_b32 v246, v248 offset:11264
	s_waitcnt lgkmcnt(3)
	v_mov_b32_e32 v121, v247
	v_lshlrev_b32_e32 v120, 16, v121
	v_and_b32_e32 v121, 0xffff0000, v121
	v_pk_fma_f32 v[122:123], v[86:87], v[120:121], v[124:125]
	v_pk_fma_f32 v[124:125], v[88:89], v[120:121], v[128:129]
	v_pk_fma_f32 v[128:129], v[90:91], v[120:121], v[166:167]
	v_pk_fma_f32 v[166:167], v[92:93], v[120:121], v[168:169]
	v_pk_fma_f32 v[168:169], v[94:95], v[120:121], v[170:171]
	v_pk_fma_f32 v[170:171], v[96:97], v[120:121], v[172:173]
	v_pk_fma_f32 v[172:173], v[98:99], v[120:121], v[174:175]
	v_pk_fma_f32 v[174:175], v[100:101], v[120:121], v[176:177]
	v_pk_fma_f32 v[176:177], v[102:103], v[120:121], v[178:179]
	v_pk_fma_f32 v[178:179], v[104:105], v[120:121], v[180:181]
	v_pk_fma_f32 v[180:181], v[106:107], v[120:121], v[182:183]
	v_pk_fma_f32 v[182:183], v[108:109], v[120:121], v[184:185]
	v_pk_fma_f32 v[184:185], v[110:111], v[120:121], v[186:187]
	v_pk_fma_f32 v[186:187], v[112:113], v[120:121], v[188:189]
	v_pk_fma_f32 v[188:189], v[114:115], v[120:121], v[190:191]
	v_pk_fma_f32 v[116:117], v[116:117], v[120:121], v[118:119]
	s_nop 0
	ds_read_b32 v247, v248 offset:11776
	s_waitcnt lgkmcnt(3)
	v_mov_b32_e32 v119, v244
	v_lshlrev_b32_e32 v118, 16, v119
	v_and_b32_e32 v119, 0xffff0000, v119
	v_pk_fma_f32 v[120:121], v[84:85], v[118:119], v[122:123]
	v_pk_fma_f32 v[122:123], v[86:87], v[118:119], v[124:125]
	v_pk_fma_f32 v[124:125], v[88:89], v[118:119], v[128:129]
	v_pk_fma_f32 v[128:129], v[90:91], v[118:119], v[166:167]
	v_pk_fma_f32 v[166:167], v[92:93], v[118:119], v[168:169]
	v_pk_fma_f32 v[168:169], v[94:95], v[118:119], v[170:171]
	v_pk_fma_f32 v[170:171], v[96:97], v[118:119], v[172:173]
	v_pk_fma_f32 v[172:173], v[98:99], v[118:119], v[174:175]
	v_pk_fma_f32 v[174:175], v[100:101], v[118:119], v[176:177]
	v_pk_fma_f32 v[176:177], v[102:103], v[118:119], v[178:179]
	v_pk_fma_f32 v[178:179], v[104:105], v[118:119], v[180:181]
	v_pk_fma_f32 v[180:181], v[106:107], v[118:119], v[182:183]
	v_pk_fma_f32 v[182:183], v[108:109], v[118:119], v[184:185]
	v_pk_fma_f32 v[184:185], v[110:111], v[118:119], v[186:187]
	v_pk_fma_f32 v[186:187], v[112:113], v[118:119], v[188:189]
	v_pk_fma_f32 v[114:115], v[114:115], v[118:119], v[116:117]
	s_nop 0
	ds_read_b32 v244, v248 offset:12288
	s_waitcnt lgkmcnt(3)
	v_mov_b32_e32 v117, v245
	v_lshlrev_b32_e32 v116, 16, v117
	v_and_b32_e32 v117, 0xffff0000, v117
	v_pk_fma_f32 v[118:119], v[82:83], v[116:117], v[120:121]
	v_pk_fma_f32 v[120:121], v[84:85], v[116:117], v[122:123]
	v_pk_fma_f32 v[122:123], v[86:87], v[116:117], v[124:125]
	v_pk_fma_f32 v[124:125], v[88:89], v[116:117], v[128:129]
	v_pk_fma_f32 v[128:129], v[90:91], v[116:117], v[166:167]
	v_pk_fma_f32 v[166:167], v[92:93], v[116:117], v[168:169]
	v_pk_fma_f32 v[168:169], v[94:95], v[116:117], v[170:171]
	v_pk_fma_f32 v[170:171], v[96:97], v[116:117], v[172:173]
	v_pk_fma_f32 v[172:173], v[98:99], v[116:117], v[174:175]
	v_pk_fma_f32 v[174:175], v[100:101], v[116:117], v[176:177]
	v_pk_fma_f32 v[176:177], v[102:103], v[116:117], v[178:179]
	v_pk_fma_f32 v[178:179], v[104:105], v[116:117], v[180:181]
	v_pk_fma_f32 v[180:181], v[106:107], v[116:117], v[182:183]
	v_pk_fma_f32 v[182:183], v[108:109], v[116:117], v[184:185]
	v_pk_fma_f32 v[184:185], v[110:111], v[116:117], v[186:187]
	v_pk_fma_f32 v[112:113], v[112:113], v[116:117], v[114:115]
	s_nop 0
	ds_read_b32 v245, v248 offset:12800
	s_waitcnt lgkmcnt(3)
	v_mov_b32_e32 v115, v246
	v_lshlrev_b32_e32 v114, 16, v115
	v_and_b32_e32 v115, 0xffff0000, v115
	v_pk_fma_f32 v[116:117], v[80:81], v[114:115], v[118:119]
	v_pk_fma_f32 v[118:119], v[82:83], v[114:115], v[120:121]
	v_pk_fma_f32 v[120:121], v[84:85], v[114:115], v[122:123]
	v_pk_fma_f32 v[122:123], v[86:87], v[114:115], v[124:125]
	v_pk_fma_f32 v[124:125], v[88:89], v[114:115], v[128:129]
	v_pk_fma_f32 v[128:129], v[90:91], v[114:115], v[166:167]
	v_pk_fma_f32 v[166:167], v[92:93], v[114:115], v[168:169]
	v_pk_fma_f32 v[168:169], v[94:95], v[114:115], v[170:171]
	v_pk_fma_f32 v[170:171], v[96:97], v[114:115], v[172:173]
	v_pk_fma_f32 v[172:173], v[98:99], v[114:115], v[174:175]
	v_pk_fma_f32 v[174:175], v[100:101], v[114:115], v[176:177]
	v_pk_fma_f32 v[176:177], v[102:103], v[114:115], v[178:179]
	v_pk_fma_f32 v[178:179], v[104:105], v[114:115], v[180:181]
	v_pk_fma_f32 v[180:181], v[106:107], v[114:115], v[182:183]
	v_pk_fma_f32 v[182:183], v[108:109], v[114:115], v[184:185]
	v_pk_fma_f32 v[110:111], v[110:111], v[114:115], v[112:113]
	s_nop 0
	ds_read_b32 v246, v248 offset:13312
	s_waitcnt lgkmcnt(3)
	v_mov_b32_e32 v113, v247
	v_lshlrev_b32_e32 v112, 16, v113
	v_and_b32_e32 v113, 0xffff0000, v113
	v_pk_fma_f32 v[114:115], v[78:79], v[112:113], v[116:117]
	v_pk_fma_f32 v[116:117], v[80:81], v[112:113], v[118:119]
	v_pk_fma_f32 v[118:119], v[82:83], v[112:113], v[120:121]
	v_pk_fma_f32 v[120:121], v[84:85], v[112:113], v[122:123]
	v_pk_fma_f32 v[122:123], v[86:87], v[112:113], v[124:125]
	v_pk_fma_f32 v[124:125], v[88:89], v[112:113], v[128:129]
	v_pk_fma_f32 v[128:129], v[90:91], v[112:113], v[166:167]
	v_pk_fma_f32 v[166:167], v[92:93], v[112:113], v[168:169]
	v_pk_fma_f32 v[168:169], v[94:95], v[112:113], v[170:171]
	v_pk_fma_f32 v[170:171], v[96:97], v[112:113], v[172:173]
	v_pk_fma_f32 v[172:173], v[98:99], v[112:113], v[174:175]
	v_pk_fma_f32 v[174:175], v[100:101], v[112:113], v[176:177]
	v_pk_fma_f32 v[176:177], v[102:103], v[112:113], v[178:179]
	v_pk_fma_f32 v[178:179], v[104:105], v[112:113], v[180:181]
	v_pk_fma_f32 v[180:181], v[106:107], v[112:113], v[182:183]
	v_pk_fma_f32 v[108:109], v[108:109], v[112:113], v[110:111]
	s_nop 0
	ds_read_b32 v247, v248 offset:13824
	s_waitcnt lgkmcnt(3)
	v_mov_b32_e32 v111, v244
	v_lshlrev_b32_e32 v110, 16, v111
	v_and_b32_e32 v111, 0xffff0000, v111
	v_pk_fma_f32 v[112:113], v[76:77], v[110:111], v[114:115]
	v_pk_fma_f32 v[114:115], v[78:79], v[110:111], v[116:117]
	v_pk_fma_f32 v[116:117], v[80:81], v[110:111], v[118:119]
	v_pk_fma_f32 v[118:119], v[82:83], v[110:111], v[120:121]
	v_pk_fma_f32 v[120:121], v[84:85], v[110:111], v[122:123]
	v_pk_fma_f32 v[122:123], v[86:87], v[110:111], v[124:125]
	v_pk_fma_f32 v[124:125], v[88:89], v[110:111], v[128:129]
	v_pk_fma_f32 v[128:129], v[90:91], v[110:111], v[166:167]
	v_pk_fma_f32 v[166:167], v[92:93], v[110:111], v[168:169]
	v_pk_fma_f32 v[168:169], v[94:95], v[110:111], v[170:171]
	v_pk_fma_f32 v[170:171], v[96:97], v[110:111], v[172:173]
	v_pk_fma_f32 v[172:173], v[98:99], v[110:111], v[174:175]
	v_pk_fma_f32 v[174:175], v[100:101], v[110:111], v[176:177]
	v_pk_fma_f32 v[176:177], v[102:103], v[110:111], v[178:179]
	v_pk_fma_f32 v[178:179], v[104:105], v[110:111], v[180:181]
	v_pk_fma_f32 v[106:107], v[106:107], v[110:111], v[108:109]
	s_nop 0
	ds_read_b32 v244, v248 offset:14336
	s_waitcnt lgkmcnt(3)
	v_mov_b32_e32 v109, v245
	v_lshlrev_b32_e32 v108, 16, v109
	v_and_b32_e32 v109, 0xffff0000, v109
	v_pk_fma_f32 v[110:111], v[74:75], v[108:109], v[112:113]
	v_pk_fma_f32 v[112:113], v[76:77], v[108:109], v[114:115]
	v_pk_fma_f32 v[114:115], v[78:79], v[108:109], v[116:117]
	v_pk_fma_f32 v[116:117], v[80:81], v[108:109], v[118:119]
	v_pk_fma_f32 v[118:119], v[82:83], v[108:109], v[120:121]
	v_pk_fma_f32 v[120:121], v[84:85], v[108:109], v[122:123]
	v_pk_fma_f32 v[122:123], v[86:87], v[108:109], v[124:125]
	v_pk_fma_f32 v[124:125], v[88:89], v[108:109], v[128:129]
	v_pk_fma_f32 v[128:129], v[90:91], v[108:109], v[166:167]
	v_pk_fma_f32 v[166:167], v[92:93], v[108:109], v[168:169]
	v_pk_fma_f32 v[168:169], v[94:95], v[108:109], v[170:171]
	v_pk_fma_f32 v[170:171], v[96:97], v[108:109], v[172:173]
	v_pk_fma_f32 v[172:173], v[98:99], v[108:109], v[174:175]
	v_pk_fma_f32 v[174:175], v[100:101], v[108:109], v[176:177]
	v_pk_fma_f32 v[176:177], v[102:103], v[108:109], v[178:179]
	v_pk_fma_f32 v[104:105], v[104:105], v[108:109], v[106:107]
	s_nop 0
	ds_read_b32 v245, v248 offset:14848
	s_waitcnt lgkmcnt(3)
	v_mov_b32_e32 v107, v246
	v_lshlrev_b32_e32 v106, 16, v107
	v_and_b32_e32 v107, 0xffff0000, v107
	v_pk_fma_f32 v[108:109], v[72:73], v[106:107], v[110:111]
	v_pk_fma_f32 v[110:111], v[74:75], v[106:107], v[112:113]
	v_pk_fma_f32 v[112:113], v[76:77], v[106:107], v[114:115]
	v_pk_fma_f32 v[114:115], v[78:79], v[106:107], v[116:117]
	v_pk_fma_f32 v[116:117], v[80:81], v[106:107], v[118:119]
	v_pk_fma_f32 v[118:119], v[82:83], v[106:107], v[120:121]
	v_pk_fma_f32 v[120:121], v[84:85], v[106:107], v[122:123]
	v_pk_fma_f32 v[122:123], v[86:87], v[106:107], v[124:125]
	v_pk_fma_f32 v[124:125], v[88:89], v[106:107], v[128:129]
	v_pk_fma_f32 v[128:129], v[90:91], v[106:107], v[166:167]
	v_pk_fma_f32 v[166:167], v[92:93], v[106:107], v[168:169]
	v_pk_fma_f32 v[168:169], v[94:95], v[106:107], v[170:171]
	v_pk_fma_f32 v[170:171], v[96:97], v[106:107], v[172:173]
	v_pk_fma_f32 v[172:173], v[98:99], v[106:107], v[174:175]
	v_pk_fma_f32 v[174:175], v[100:101], v[106:107], v[176:177]
	v_pk_fma_f32 v[102:103], v[102:103], v[106:107], v[104:105]
	s_nop 0
	ds_read_b32 v246, v248 offset:15360
	s_waitcnt lgkmcnt(3)
	v_mov_b32_e32 v105, v247
	v_lshlrev_b32_e32 v104, 16, v105
	v_and_b32_e32 v105, 0xffff0000, v105
	v_pk_fma_f32 v[106:107], v[70:71], v[104:105], v[108:109]
	v_pk_fma_f32 v[108:109], v[72:73], v[104:105], v[110:111]
	v_pk_fma_f32 v[110:111], v[74:75], v[104:105], v[112:113]
	v_pk_fma_f32 v[112:113], v[76:77], v[104:105], v[114:115]
	v_pk_fma_f32 v[114:115], v[78:79], v[104:105], v[116:117]
	v_pk_fma_f32 v[116:117], v[80:81], v[104:105], v[118:119]
	v_pk_fma_f32 v[118:119], v[82:83], v[104:105], v[120:121]
	v_pk_fma_f32 v[120:121], v[84:85], v[104:105], v[122:123]
	v_pk_fma_f32 v[122:123], v[86:87], v[104:105], v[124:125]
	v_pk_fma_f32 v[124:125], v[88:89], v[104:105], v[128:129]
	v_pk_fma_f32 v[128:129], v[90:91], v[104:105], v[166:167]
	v_pk_fma_f32 v[166:167], v[92:93], v[104:105], v[168:169]
	v_pk_fma_f32 v[168:169], v[94:95], v[104:105], v[170:171]
	v_pk_fma_f32 v[170:171], v[96:97], v[104:105], v[172:173]
	v_pk_fma_f32 v[172:173], v[98:99], v[104:105], v[174:175]
	v_pk_fma_f32 v[100:101], v[100:101], v[104:105], v[102:103]
	s_nop 0
	ds_read_b32 v247, v248 offset:15872
	s_waitcnt lgkmcnt(3)
	v_mov_b32_e32 v103, v244
	v_lshlrev_b32_e32 v102, 16, v103
	v_and_b32_e32 v103, 0xffff0000, v103
	v_pk_fma_f32 v[104:105], v[68:69], v[102:103], v[106:107]
	v_pk_fma_f32 v[106:107], v[70:71], v[102:103], v[108:109]
	v_pk_fma_f32 v[108:109], v[72:73], v[102:103], v[110:111]
	v_pk_fma_f32 v[110:111], v[74:75], v[102:103], v[112:113]
	v_pk_fma_f32 v[112:113], v[76:77], v[102:103], v[114:115]
	v_pk_fma_f32 v[114:115], v[78:79], v[102:103], v[116:117]
	v_pk_fma_f32 v[116:117], v[80:81], v[102:103], v[118:119]
	v_pk_fma_f32 v[118:119], v[82:83], v[102:103], v[120:121]
	v_pk_fma_f32 v[120:121], v[84:85], v[102:103], v[122:123]
	v_pk_fma_f32 v[122:123], v[86:87], v[102:103], v[124:125]
	v_pk_fma_f32 v[124:125], v[88:89], v[102:103], v[128:129]
	v_pk_fma_f32 v[128:129], v[90:91], v[102:103], v[166:167]
	v_pk_fma_f32 v[166:167], v[92:93], v[102:103], v[168:169]
	v_pk_fma_f32 v[168:169], v[94:95], v[102:103], v[170:171]
	v_pk_fma_f32 v[170:171], v[96:97], v[102:103], v[172:173]
	v_pk_fma_f32 v[98:99], v[98:99], v[102:103], v[100:101]
	s_nop 0
	ds_read_b32 v244, v248 offset:16384
	s_waitcnt lgkmcnt(3)
	v_mov_b32_e32 v101, v245
	v_lshlrev_b32_e32 v100, 16, v101
	v_and_b32_e32 v101, 0xffff0000, v101
	v_pk_fma_f32 v[102:103], v[66:67], v[100:101], v[104:105]
	v_pk_fma_f32 v[104:105], v[68:69], v[100:101], v[106:107]
	v_pk_fma_f32 v[106:107], v[70:71], v[100:101], v[108:109]
	v_pk_fma_f32 v[108:109], v[72:73], v[100:101], v[110:111]
	v_pk_fma_f32 v[110:111], v[74:75], v[100:101], v[112:113]
	v_pk_fma_f32 v[112:113], v[76:77], v[100:101], v[114:115]
	v_pk_fma_f32 v[114:115], v[78:79], v[100:101], v[116:117]
	v_pk_fma_f32 v[116:117], v[80:81], v[100:101], v[118:119]
	v_pk_fma_f32 v[118:119], v[82:83], v[100:101], v[120:121]
	v_pk_fma_f32 v[120:121], v[84:85], v[100:101], v[122:123]
	v_pk_fma_f32 v[122:123], v[86:87], v[100:101], v[124:125]
	v_pk_fma_f32 v[124:125], v[88:89], v[100:101], v[128:129]
	v_pk_fma_f32 v[128:129], v[90:91], v[100:101], v[166:167]
	v_pk_fma_f32 v[166:167], v[92:93], v[100:101], v[168:169]
	v_pk_fma_f32 v[168:169], v[94:95], v[100:101], v[170:171]
	v_pk_fma_f32 v[98:99], v[96:97], v[100:101], v[98:99]
	s_nop 0
	ds_read_b32 v245, v248 offset:16896
	s_waitcnt lgkmcnt(3)
	v_mov_b32_e32 v96, v246
	v_lshlrev_b32_e32 v100, 16, v96
	v_and_b32_e32 v101, 0xffff0000, v96
	v_pk_fma_f32 v[96:97], v[64:65], v[100:101], v[102:103]
	v_pk_fma_f32 v[102:103], v[66:67], v[100:101], v[104:105]
	v_pk_fma_f32 v[104:105], v[68:69], v[100:101], v[106:107]
	v_pk_fma_f32 v[106:107], v[70:71], v[100:101], v[108:109]
	v_pk_fma_f32 v[108:109], v[72:73], v[100:101], v[110:111]
	v_pk_fma_f32 v[110:111], v[74:75], v[100:101], v[112:113]
	v_pk_fma_f32 v[112:113], v[76:77], v[100:101], v[114:115]
	v_pk_fma_f32 v[114:115], v[78:79], v[100:101], v[116:117]
	v_pk_fma_f32 v[116:117], v[80:81], v[100:101], v[118:119]
	v_pk_fma_f32 v[118:119], v[82:83], v[100:101], v[120:121]
	v_pk_fma_f32 v[120:121], v[84:85], v[100:101], v[122:123]
	v_pk_fma_f32 v[122:123], v[86:87], v[100:101], v[124:125]
	v_pk_fma_f32 v[124:125], v[88:89], v[100:101], v[128:129]
	v_pk_fma_f32 v[128:129], v[90:91], v[100:101], v[166:167]
	v_pk_fma_f32 v[166:167], v[92:93], v[100:101], v[168:169]
	v_pk_fma_f32 v[98:99], v[94:95], v[100:101], v[98:99]
	s_nop 0
	ds_read_b32 v246, v248 offset:17408
	s_waitcnt lgkmcnt(3)
	v_mov_b32_e32 v94, v247
	v_lshlrev_b32_e32 v100, 16, v94
	v_and_b32_e32 v101, 0xffff0000, v94
	v_pk_fma_f32 v[94:95], v[64:65], v[100:101], v[102:103]
	v_pk_fma_f32 v[102:103], v[66:67], v[100:101], v[104:105]
	v_pk_fma_f32 v[104:105], v[68:69], v[100:101], v[106:107]
	v_pk_fma_f32 v[106:107], v[70:71], v[100:101], v[108:109]
	v_pk_fma_f32 v[108:109], v[72:73], v[100:101], v[110:111]
	v_pk_fma_f32 v[110:111], v[74:75], v[100:101], v[112:113]
	v_pk_fma_f32 v[112:113], v[76:77], v[100:101], v[114:115]
	v_pk_fma_f32 v[114:115], v[78:79], v[100:101], v[116:117]
	v_pk_fma_f32 v[116:117], v[80:81], v[100:101], v[118:119]
	v_pk_fma_f32 v[118:119], v[82:83], v[100:101], v[120:121]
	v_pk_fma_f32 v[120:121], v[84:85], v[100:101], v[122:123]
	v_pk_fma_f32 v[122:123], v[86:87], v[100:101], v[124:125]
	v_pk_fma_f32 v[124:125], v[88:89], v[100:101], v[128:129]
	v_pk_fma_f32 v[128:129], v[90:91], v[100:101], v[166:167]
	v_pk_fma_f32 v[98:99], v[92:93], v[100:101], v[98:99]
	s_nop 0
	ds_read_b32 v247, v248 offset:17920
	s_waitcnt lgkmcnt(3)
	v_mov_b32_e32 v92, v244
	v_lshlrev_b32_e32 v100, 16, v92
	v_and_b32_e32 v101, 0xffff0000, v92
	v_pk_fma_f32 v[92:93], v[64:65], v[100:101], v[102:103]
	v_pk_fma_f32 v[102:103], v[66:67], v[100:101], v[104:105]
	v_pk_fma_f32 v[104:105], v[68:69], v[100:101], v[106:107]
	v_pk_fma_f32 v[106:107], v[70:71], v[100:101], v[108:109]
	v_pk_fma_f32 v[108:109], v[72:73], v[100:101], v[110:111]
	v_pk_fma_f32 v[110:111], v[74:75], v[100:101], v[112:113]
	v_pk_fma_f32 v[112:113], v[76:77], v[100:101], v[114:115]
	v_pk_fma_f32 v[114:115], v[78:79], v[100:101], v[116:117]
	v_pk_fma_f32 v[116:117], v[80:81], v[100:101], v[118:119]
	v_pk_fma_f32 v[118:119], v[82:83], v[100:101], v[120:121]
	v_pk_fma_f32 v[120:121], v[84:85], v[100:101], v[122:123]
	v_pk_fma_f32 v[122:123], v[86:87], v[100:101], v[124:125]
	v_pk_fma_f32 v[124:125], v[88:89], v[100:101], v[128:129]
	v_pk_fma_f32 v[98:99], v[90:91], v[100:101], v[98:99]
	s_nop 0
	ds_read_b32 v244, v248 offset:18432
	s_waitcnt lgkmcnt(3)
	v_mov_b32_e32 v90, v245
	v_lshlrev_b32_e32 v100, 16, v90
	v_and_b32_e32 v101, 0xffff0000, v90
	v_pk_fma_f32 v[90:91], v[64:65], v[100:101], v[102:103]
	v_pk_fma_f32 v[102:103], v[66:67], v[100:101], v[104:105]
	v_pk_fma_f32 v[104:105], v[68:69], v[100:101], v[106:107]
	v_pk_fma_f32 v[106:107], v[70:71], v[100:101], v[108:109]
	v_pk_fma_f32 v[108:109], v[72:73], v[100:101], v[110:111]
	v_pk_fma_f32 v[110:111], v[74:75], v[100:101], v[112:113]
	v_pk_fma_f32 v[112:113], v[76:77], v[100:101], v[114:115]
	v_pk_fma_f32 v[114:115], v[78:79], v[100:101], v[116:117]
	v_pk_fma_f32 v[116:117], v[80:81], v[100:101], v[118:119]
	v_pk_fma_f32 v[118:119], v[82:83], v[100:101], v[120:121]
	v_pk_fma_f32 v[120:121], v[84:85], v[100:101], v[122:123]
	v_pk_fma_f32 v[122:123], v[86:87], v[100:101], v[124:125]
	v_pk_fma_f32 v[98:99], v[88:89], v[100:101], v[98:99]
	s_nop 0
	ds_read_b32 v245, v248 offset:18944
	s_waitcnt lgkmcnt(3)
	v_mov_b32_e32 v88, v246
	v_lshlrev_b32_e32 v100, 16, v88
	v_and_b32_e32 v101, 0xffff0000, v88
	v_pk_fma_f32 v[88:89], v[64:65], v[100:101], v[102:103]
	v_pk_fma_f32 v[102:103], v[66:67], v[100:101], v[104:105]
	v_pk_fma_f32 v[104:105], v[68:69], v[100:101], v[106:107]
	v_pk_fma_f32 v[106:107], v[70:71], v[100:101], v[108:109]
	v_pk_fma_f32 v[108:109], v[72:73], v[100:101], v[110:111]
	v_pk_fma_f32 v[110:111], v[74:75], v[100:101], v[112:113]
	v_pk_fma_f32 v[112:113], v[76:77], v[100:101], v[114:115]
	v_pk_fma_f32 v[114:115], v[78:79], v[100:101], v[116:117]
	v_pk_fma_f32 v[116:117], v[80:81], v[100:101], v[118:119]
	v_pk_fma_f32 v[118:119], v[82:83], v[100:101], v[120:121]
	v_pk_fma_f32 v[120:121], v[84:85], v[100:101], v[122:123]
	v_pk_fma_f32 v[98:99], v[86:87], v[100:101], v[98:99]
	s_nop 0
	ds_read_b32 v246, v248 offset:19456
	s_waitcnt lgkmcnt(3)
	v_mov_b32_e32 v86, v247
	v_lshlrev_b32_e32 v100, 16, v86
	v_and_b32_e32 v101, 0xffff0000, v86
	v_pk_fma_f32 v[86:87], v[64:65], v[100:101], v[102:103]
	v_pk_fma_f32 v[102:103], v[66:67], v[100:101], v[104:105]
	v_pk_fma_f32 v[104:105], v[68:69], v[100:101], v[106:107]
	v_pk_fma_f32 v[106:107], v[70:71], v[100:101], v[108:109]
	v_pk_fma_f32 v[108:109], v[72:73], v[100:101], v[110:111]
	v_pk_fma_f32 v[110:111], v[74:75], v[100:101], v[112:113]
	v_pk_fma_f32 v[112:113], v[76:77], v[100:101], v[114:115]
	v_pk_fma_f32 v[114:115], v[78:79], v[100:101], v[116:117]
	v_pk_fma_f32 v[116:117], v[80:81], v[100:101], v[118:119]
	v_pk_fma_f32 v[118:119], v[82:83], v[100:101], v[120:121]
	v_pk_fma_f32 v[98:99], v[84:85], v[100:101], v[98:99]
	s_nop 0
	ds_read_b32 v247, v248 offset:19968
	s_waitcnt lgkmcnt(3)
	v_mov_b32_e32 v84, v244
	v_lshlrev_b32_e32 v100, 16, v84
	v_and_b32_e32 v101, 0xffff0000, v84
	v_pk_fma_f32 v[84:85], v[64:65], v[100:101], v[102:103]
	v_pk_fma_f32 v[102:103], v[66:67], v[100:101], v[104:105]
	v_pk_fma_f32 v[104:105], v[68:69], v[100:101], v[106:107]
	v_pk_fma_f32 v[106:107], v[70:71], v[100:101], v[108:109]
	v_pk_fma_f32 v[108:109], v[72:73], v[100:101], v[110:111]
	v_pk_fma_f32 v[110:111], v[74:75], v[100:101], v[112:113]
	v_pk_fma_f32 v[112:113], v[76:77], v[100:101], v[114:115]
	v_pk_fma_f32 v[114:115], v[78:79], v[100:101], v[116:117]
	v_pk_fma_f32 v[116:117], v[80:81], v[100:101], v[118:119]
	v_pk_fma_f32 v[98:99], v[82:83], v[100:101], v[98:99]
	s_nop 0
	ds_read_b32 v244, v248 offset:20480
	s_waitcnt lgkmcnt(3)
	v_mov_b32_e32 v82, v245
	v_lshlrev_b32_e32 v100, 16, v82
	v_and_b32_e32 v101, 0xffff0000, v82
	v_pk_fma_f32 v[82:83], v[64:65], v[100:101], v[102:103]
	v_pk_fma_f32 v[102:103], v[66:67], v[100:101], v[104:105]
	v_pk_fma_f32 v[104:105], v[68:69], v[100:101], v[106:107]
	v_pk_fma_f32 v[106:107], v[70:71], v[100:101], v[108:109]
	v_pk_fma_f32 v[108:109], v[72:73], v[100:101], v[110:111]
	v_pk_fma_f32 v[110:111], v[74:75], v[100:101], v[112:113]
	v_pk_fma_f32 v[112:113], v[76:77], v[100:101], v[114:115]
	v_pk_fma_f32 v[114:115], v[78:79], v[100:101], v[116:117]
	v_pk_fma_f32 v[98:99], v[80:81], v[100:101], v[98:99]
	s_nop 0
	ds_read_b32 v245, v248 offset:20992
	s_waitcnt lgkmcnt(3)
	v_mov_b32_e32 v80, v246
	v_lshlrev_b32_e32 v100, 16, v80
	v_and_b32_e32 v101, 0xffff0000, v80
	v_pk_fma_f32 v[80:81], v[64:65], v[100:101], v[102:103]
	v_pk_fma_f32 v[102:103], v[66:67], v[100:101], v[104:105]
	v_pk_fma_f32 v[104:105], v[68:69], v[100:101], v[106:107]
	v_pk_fma_f32 v[106:107], v[70:71], v[100:101], v[108:109]
	v_pk_fma_f32 v[108:109], v[72:73], v[100:101], v[110:111]
	v_pk_fma_f32 v[110:111], v[74:75], v[100:101], v[112:113]
	v_pk_fma_f32 v[112:113], v[76:77], v[100:101], v[114:115]
	v_pk_fma_f32 v[98:99], v[78:79], v[100:101], v[98:99]
	s_nop 0
	ds_read_b32 v246, v248 offset:21504
	s_waitcnt lgkmcnt(3)
	v_mov_b32_e32 v78, v247
	v_lshlrev_b32_e32 v100, 16, v78
	v_and_b32_e32 v101, 0xffff0000, v78
	v_pk_fma_f32 v[78:79], v[64:65], v[100:101], v[102:103]
	v_pk_fma_f32 v[102:103], v[66:67], v[100:101], v[104:105]
	v_pk_fma_f32 v[104:105], v[68:69], v[100:101], v[106:107]
	v_pk_fma_f32 v[106:107], v[70:71], v[100:101], v[108:109]
	v_pk_fma_f32 v[108:109], v[72:73], v[100:101], v[110:111]
	v_pk_fma_f32 v[110:111], v[74:75], v[100:101], v[112:113]
	v_pk_fma_f32 v[76:77], v[76:77], v[100:101], v[98:99]
	s_nop 0
	ds_read_b32 v247, v248 offset:22016
	s_waitcnt lgkmcnt(3)
	v_mov_b32_e32 v99, v244
	v_lshlrev_b32_e32 v98, 16, v99
	v_and_b32_e32 v99, 0xffff0000, v99
	v_pk_fma_f32 v[100:101], v[64:65], v[98:99], v[102:103]
	v_pk_fma_f32 v[102:103], v[66:67], v[98:99], v[104:105]
	v_pk_fma_f32 v[104:105], v[68:69], v[98:99], v[106:107]
	v_pk_fma_f32 v[106:107], v[70:71], v[98:99], v[108:109]
	v_pk_fma_f32 v[108:109], v[72:73], v[98:99], v[110:111]
	v_pk_fma_f32 v[74:75], v[74:75], v[98:99], v[76:77]
	v_and_b32_e32 v110, 63, v156
	ds_read_b32 v244, v248 offset:22528
	s_waitcnt lgkmcnt(3)
	v_mov_b32_e32 v77, v245
	v_lshlrev_b32_e32 v76, 16, v77
	v_and_b32_e32 v77, 0xffff0000, v77
	v_pk_fma_f32 v[98:99], v[64:65], v[76:77], v[102:103]
	v_pk_fma_f32 v[102:103], v[66:67], v[76:77], v[104:105]
	v_pk_fma_f32 v[104:105], v[68:69], v[76:77], v[106:107]
	v_pk_fma_f32 v[106:107], v[70:71], v[76:77], v[108:109]
	v_pk_fma_f32 v[72:73], v[72:73], v[76:77], v[74:75]
	s_nop 0
	ds_read_b32 v245, v248 offset:23040
	s_waitcnt lgkmcnt(3)
	v_mov_b32_e32 v75, v246
	v_lshlrev_b32_e32 v74, 16, v75
	v_and_b32_e32 v75, 0xffff0000, v75
	v_pk_fma_f32 v[76:77], v[64:65], v[74:75], v[102:103]
	v_pk_fma_f32 v[102:103], v[66:67], v[74:75], v[104:105]
	v_pk_fma_f32 v[104:105], v[68:69], v[74:75], v[106:107]
	v_pk_fma_f32 v[70:71], v[70:71], v[74:75], v[72:73]
	s_nop 0
	s_waitcnt lgkmcnt(2)
	v_mov_b32_e32 v73, v247
	v_lshlrev_b32_e32 v72, 16, v73
	v_and_b32_e32 v73, 0xffff0000, v73
	v_pk_fma_f32 v[74:75], v[64:65], v[72:73], v[102:103]
	v_pk_fma_f32 v[102:103], v[66:67], v[72:73], v[104:105]
	v_pk_fma_f32 v[68:69], v[68:69], v[72:73], v[70:71]
	s_nop 0
	s_waitcnt lgkmcnt(1)
	v_mov_b32_e32 v71, v244
	v_lshlrev_b32_e32 v70, 16, v71
	v_and_b32_e32 v71, 0xffff0000, v71
	v_pk_fma_f32 v[72:73], v[64:65], v[70:71], v[102:103]
	v_pk_fma_f32 v[66:67], v[66:67], v[70:71], v[68:69]
	s_nop 0
	s_waitcnt lgkmcnt(0)
	v_mov_b32_e32 v69, v245
	v_lshlrev_b32_e32 v68, 16, v69
	v_and_b32_e32 v69, 0xffff0000, v69
	v_pk_fma_f32 v[64:65], v[64:65], v[68:69], v[66:67]
	v_lshl_add_u32 v66, v157, 3, 0
	v_lshl_add_u32 v67, v159, 10, v66
	ds_write_b64 v67, v[96:97] offset:48128
	v_lshl_add_u32 v67, v160, 10, v66
	ds_write_b64 v67, v[94:95] offset:48128
	v_lshl_add_u32 v67, v126, 10, v66
	ds_write_b64 v67, v[92:93] offset:48128
	v_lshl_add_u32 v67, v127, 10, v66
	ds_write_b64 v67, v[90:91] offset:48128
	v_lshl_add_u32 v67, v162, 10, v66
	ds_write_b64 v67, v[88:89] offset:48128
	v_lshl_add_u32 v67, v163, 10, v66
	ds_write_b64 v67, v[86:87] offset:48128
	v_lshl_add_u32 v67, v164, 10, v66
	ds_write_b64 v67, v[84:85] offset:48128
	v_lshl_add_u32 v67, v165, 10, v66
	ds_write_b64 v67, v[82:83] offset:48128
	v_lshl_add_u32 v67, v144, 10, v66
	ds_write_b64 v67, v[80:81] offset:48128
	v_lshl_add_u32 v67, v142, 10, v66
	ds_write_b64 v67, v[78:79] offset:48128
	v_lshl_add_u32 v67, v140, 10, v66
	ds_write_b64 v67, v[100:101] offset:48128
	v_lshl_add_u32 v67, v138, 10, v66
	ds_write_b64 v67, v[98:99] offset:48128
	v_lshl_add_u32 v67, v136, 10, v66
	ds_write_b64 v67, v[76:77] offset:48128
	v_lshl_add_u32 v67, v134, 10, v66
	ds_write_b64 v67, v[74:75] offset:48128
	v_lshl_add_u32 v67, v132, 10, v66
	v_lshl_add_u32 v66, v130, 10, v66
	v_lshlrev_b32_e32 v68, 4, v110
	ds_write_b64 v67, v[72:73] offset:48128
	ds_write_b64 v66, v[64:65] offset:48128
	s_waitcnt lgkmcnt(0)
	s_barrier
	global_load_dwordx4 v[64:67], v68, s[42:43]
	v_readlane_b32 s42, v255, 7
	v_readlane_b32 s43, v255, 8
	v_add_u32_e32 v106, s23, v68
	ds_read_b128 v[100:103], v106 offset:48128
	ds_read_b128 v[96:99], v106 offset:49152
	ds_read_b128 v[92:95], v106 offset:50176
	ds_read_b128 v[88:91], v106 offset:51200
	global_load_dwordx4 v[68:71], v68, s[42:43]
	s_waitcnt lgkmcnt(3)
	v_mov_b32_e32 v72, v101
	v_mov_b32_e32 v73, v102
	v_mov_b32_e32 v74, v100
	v_mov_b32_e32 v75, v103
	v_pk_add_f32 v[72:73], v[72:73], v[74:75]
	v_pk_mul_f32 v[74:75], v[100:101], v[100:101]
	v_add_f32_e32 v111, v72, v73
	v_pk_mul_f32 v[72:73], v[102:103], v[102:103]
	ds_read_b128 v[84:87], v106 offset:52224
	ds_read_b128 v[80:83], v106 offset:53248
	v_pk_mov_b32 v[76:77], v[74:75], v[72:73] op_sel:[1,0]
	v_mov_b32_e32 v75, v73
	v_pk_add_f32 v[72:73], v[76:77], v[74:75]
	s_waitcnt lgkmcnt(4)
	v_mov_b32_e32 v74, v96
	v_add_f32_e32 v112, v72, v73
	v_mov_b32_e32 v72, v97
	v_mov_b32_e32 v73, v98
	v_mov_b32_e32 v75, v99
	v_pk_add_f32 v[72:73], v[72:73], v[74:75]
	v_pk_mul_f32 v[74:75], v[96:97], v[96:97]
	v_add_f32_e32 v113, v72, v73
	v_pk_mul_f32 v[72:73], v[98:99], v[98:99]
	s_nop 0
	v_pk_mov_b32 v[76:77], v[74:75], v[72:73] op_sel:[1,0]
	v_mov_b32_e32 v75, v73
	v_pk_add_f32 v[72:73], v[76:77], v[74:75]
	s_waitcnt lgkmcnt(3)
	v_mov_b32_e32 v74, v92
	v_add_f32_e32 v114, v72, v73
	v_mov_b32_e32 v72, v93
	v_mov_b32_e32 v73, v94
	v_mov_b32_e32 v75, v95
	v_pk_add_f32 v[72:73], v[72:73], v[74:75]
	v_pk_mul_f32 v[74:75], v[92:93], v[92:93]
	v_add_f32_e32 v115, v72, v73
	v_pk_mul_f32 v[72:73], v[94:95], v[94:95]
	s_nop 0
	v_pk_mov_b32 v[76:77], v[74:75], v[72:73] op_sel:[1,0]
	v_mov_b32_e32 v75, v73
	v_pk_add_f32 v[72:73], v[76:77], v[74:75]
	s_waitcnt lgkmcnt(2)
	v_mov_b32_e32 v74, v88
	v_add_f32_e32 v116, v72, v73
	v_mov_b32_e32 v72, v89
	v_mov_b32_e32 v73, v90
	v_mov_b32_e32 v75, v91
	v_pk_add_f32 v[72:73], v[72:73], v[74:75]
	v_pk_mul_f32 v[74:75], v[88:89], v[88:89]
	v_add_f32_e32 v117, v72, v73
	v_pk_mul_f32 v[72:73], v[90:91], v[90:91]
	s_nop 0
	v_pk_mov_b32 v[76:77], v[74:75], v[72:73] op_sel:[1,0]
	v_mov_b32_e32 v75, v73
	v_pk_add_f32 v[72:73], v[76:77], v[74:75]
	s_waitcnt lgkmcnt(1)
	v_mov_b32_e32 v74, v84
	v_add_f32_e32 v118, v72, v73
	v_mov_b32_e32 v72, v85
	v_mov_b32_e32 v73, v86
	v_mov_b32_e32 v75, v87
	v_pk_add_f32 v[72:73], v[72:73], v[74:75]
	v_pk_mul_f32 v[74:75], v[84:85], v[84:85]
	v_add_f32_e32 v119, v72, v73
	v_pk_mul_f32 v[72:73], v[86:87], v[86:87]
	s_nop 0
	v_pk_mov_b32 v[76:77], v[74:75], v[72:73] op_sel:[1,0]
	v_mov_b32_e32 v75, v73
	v_pk_add_f32 v[72:73], v[76:77], v[74:75]
	s_waitcnt lgkmcnt(0)
	v_mov_b32_e32 v74, v80
	v_add_f32_e32 v120, v72, v73
	v_mov_b32_e32 v72, v81
	v_mov_b32_e32 v73, v82
	v_mov_b32_e32 v75, v83
	ds_read_b128 v[76:79], v106 offset:54272
	v_pk_add_f32 v[72:73], v[72:73], v[74:75]
	v_pk_mul_f32 v[74:75], v[80:81], v[80:81]
	v_add_f32_e32 v121, v72, v73
	v_pk_mul_f32 v[72:73], v[82:83], v[82:83]
	s_nop 0
	v_pk_mov_b32 v[104:105], v[74:75], v[72:73] op_sel:[1,0]
	v_mov_b32_e32 v75, v73
	v_pk_add_f32 v[72:73], v[104:105], v[74:75]
	s_nop 0
	v_add_f32_e32 v122, v72, v73
	ds_read_b128 v[72:75], v106 offset:55296
	s_waitcnt lgkmcnt(1)
	v_mov_b32_e32 v104, v77
	v_mov_b32_e32 v105, v78
	v_mov_b32_e32 v106, v76
	v_mov_b32_e32 v107, v79
	v_pk_add_f32 v[104:105], v[104:105], v[106:107]
	v_pk_mul_f32 v[106:107], v[76:77], v[76:77]
	v_add_f32_e32 v123, v104, v105
	v_pk_mul_f32 v[104:105], v[78:79], v[78:79]
	s_nop 0
	v_pk_mov_b32 v[108:109], v[106:107], v[104:105] op_sel:[1,0]
	v_mov_b32_e32 v107, v105
	v_pk_add_f32 v[104:105], v[108:109], v[106:107]
	s_waitcnt lgkmcnt(0)
	v_mov_b32_e32 v106, v72
	v_add_f32_e32 v124, v104, v105
	v_mov_b32_e32 v104, v73
	v_mov_b32_e32 v105, v74
	v_mov_b32_e32 v107, v75
	v_pk_add_f32 v[104:105], v[104:105], v[106:107]
	v_pk_mul_f32 v[106:107], v[72:73], v[72:73]
	v_add_f32_e32 v125, v104, v105
	v_pk_mul_f32 v[104:105], v[74:75], v[74:75]
	s_nop 0
	v_pk_mov_b32 v[108:109], v[106:107], v[104:105] op_sel:[1,0]
	v_mov_b32_e32 v107, v105
	v_pk_add_f32 v[104:105], v[108:109], v[106:107]
	v_add_f32_dpp v106, v112, v112 quad_perm:[1,0,3,2] row_mask:0xf bank_mask:0xf bound_ctrl:1
	v_add_f32_e32 v104, v104, v105
	v_add_f32_dpp v105, v111, v111 quad_perm:[1,0,3,2] row_mask:0xf bank_mask:0xf bound_ctrl:1
	v_add_f32_dpp v111, v116, v116 quad_perm:[1,0,3,2] row_mask:0xf bank_mask:0xf bound_ctrl:1
	v_add_f32_dpp v104, v104, v104 quad_perm:[1,0,3,2] row_mask:0xf bank_mask:0xf bound_ctrl:1
	v_add_f32_dpp v105, v105, v105 quad_perm:[2,3,0,1] row_mask:0xf bank_mask:0xf bound_ctrl:1
	v_add_f32_dpp v116, v121, v121 quad_perm:[1,0,3,2] row_mask:0xf bank_mask:0xf bound_ctrl:1
	v_add_f32_dpp v104, v104, v104 quad_perm:[2,3,0,1] row_mask:0xf bank_mask:0xf bound_ctrl:1
	v_add_f32_dpp v105, v105, v105 row_half_mirror row_mask:0xf bank_mask:0xf bound_ctrl:1
	v_add_f32_dpp v106, v106, v106 quad_perm:[2,3,0,1] row_mask:0xf bank_mask:0xf bound_ctrl:1
	v_add_f32_dpp v121, v104, v104 row_half_mirror row_mask:0xf bank_mask:0xf bound_ctrl:1
	v_add_f32_dpp v104, v105, v105 row_mirror row_mask:0xf bank_mask:0xf bound_ctrl:1
	v_add_f32_dpp v106, v106, v106 row_half_mirror row_mask:0xf bank_mask:0xf bound_ctrl:1
	v_readlane_b32 s23, v104, 16
	v_readlane_b32 s44, v104, 48
	v_add_f32_dpp v107, v113, v113 quad_perm:[1,0,3,2] row_mask:0xf bank_mask:0xf bound_ctrl:1
	v_add_f32_dpp v112, v117, v117 quad_perm:[1,0,3,2] row_mask:0xf bank_mask:0xf bound_ctrl:1
	v_add_f32_dpp v117, v122, v122 quad_perm:[1,0,3,2] row_mask:0xf bank_mask:0xf bound_ctrl:1
	v_add_f32_dpp v122, v106, v106 row_mirror row_mask:0xf bank_mask:0xf bound_ctrl:1
	v_readlane_b32 s42, v104, 0
	v_readlane_b32 s43, v104, 32
	v_mov_b32_e32 v104, s23
	v_mov_b32_e32 v105, s44
	v_add_f32_dpp v108, v114, v114 quad_perm:[1,0,3,2] row_mask:0xf bank_mask:0xf bound_ctrl:1
	v_add_f32_dpp v109, v115, v115 quad_perm:[1,0,3,2] row_mask:0xf bank_mask:0xf bound_ctrl:1
	v_add_f32_dpp v107, v107, v107 quad_perm:[2,3,0,1] row_mask:0xf bank_mask:0xf bound_ctrl:1
	v_pk_add_f32 v[104:105], s[42:43], v[104:105]
	v_readlane_b32 s42, v122, 16
	v_add_f32_dpp v108, v108, v108 quad_perm:[2,3,0,1] row_mask:0xf bank_mask:0xf bound_ctrl:1
	v_add_f32_dpp v109, v109, v109 quad_perm:[2,3,0,1] row_mask:0xf bank_mask:0xf bound_ctrl:1
	v_add_f32_dpp v107, v107, v107 row_half_mirror row_mask:0xf bank_mask:0xf bound_ctrl:1
	v_readlane_b32 s23, v122, 0
	v_mov_b32_e32 v106, s42
	v_readlane_b32 s42, v122, 48
	v_add_f32_dpp v113, v118, v118 quad_perm:[1,0,3,2] row_mask:0xf bank_mask:0xf bound_ctrl:1
	v_add_f32_dpp v118, v123, v123 quad_perm:[1,0,3,2] row_mask:0xf bank_mask:0xf bound_ctrl:1
	v_add_f32_dpp v108, v108, v108 row_half_mirror row_mask:0xf bank_mask:0xf bound_ctrl:1
	v_add_f32_dpp v109, v109, v109 row_half_mirror row_mask:0xf bank_mask:0xf bound_ctrl:1
	v_add_f32_dpp v123, v107, v107 row_mirror row_mask:0xf bank_mask:0xf bound_ctrl:1
	v_add_f32_e32 v106, s23, v106
	v_readlane_b32 s23, v122, 32
	v_mov_b32_e32 v107, s42
	v_add_f32_dpp v114, v119, v119 quad_perm:[1,0,3,2] row_mask:0xf bank_mask:0xf bound_ctrl:1
	v_add_f32_dpp v115, v120, v120 quad_perm:[1,0,3,2] row_mask:0xf bank_mask:0xf bound_ctrl:1
	v_add_f32_dpp v119, v124, v124 quad_perm:[1,0,3,2] row_mask:0xf bank_mask:0xf bound_ctrl:1
	v_add_f32_dpp v120, v125, v125 quad_perm:[1,0,3,2] row_mask:0xf bank_mask:0xf bound_ctrl:1
	v_add_f32_dpp v124, v108, v108 row_mirror row_mask:0xf bank_mask:0xf bound_ctrl:1
	v_add_f32_dpp v125, v109, v109 row_mirror row_mask:0xf bank_mask:0xf bound_ctrl:1
	v_add_f32_e32 v108, s23, v107
	v_mov_b32_e32 v107, v104
	v_mov_b32_e32 v109, v105
	v_pk_add_f32 v[104:105], v[106:107], v[108:109]
	v_readlane_b32 s23, v123, 16
	v_pk_mul_f32 v[104:105], v[104:105], s[46:47] op_sel_hi:[1,0]
	v_readlane_b32 s44, v123, 48
	v_fma_f32 v106, -v105, v105, v104
	v_max_f32_e32 v106, 0, v106
	v_add_f32_e32 v106, 0x3727c5ac, v106
	v_rsq_f32_e32 v106, v106
	v_pk_add_f32 v[100:101], v[100:101], v[104:105] op_sel:[0,1] neg_lo:[0,1] neg_hi:[0,1]
	v_pk_add_f32 v[102:103], v[102:103], v[104:105] op_sel:[0,1] neg_lo:[0,1] neg_hi:[0,1]
	v_readlane_b32 s42, v123, 0
	v_pk_mul_f32 v[100:101], v[100:101], v[106:107] op_sel_hi:[1,0]
	v_readlane_b32 s43, v123, 32
	s_waitcnt vmcnt(0)
	v_pk_fma_f32 v[100:101], v[64:65], v[100:101], v[68:69]
	v_add_f32_dpp v111, v111, v111 quad_perm:[2,3,0,1] row_mask:0xf bank_mask:0xf bound_ctrl:1
	v_mul_f32_e32 v107, 0xbfb8aa3b, v100
	v_exp_f32_e32 v107, v107
	v_mul_f32_e32 v108, 0xbfb8aa3b, v101
	v_exp_f32_e32 v109, v108
	v_add_f32_dpp v111, v111, v111 row_half_mirror row_mask:0xf bank_mask:0xf bound_ctrl:1
	v_add_f32_e32 v107, 1.0, v107
	v_rcp_f32_e32 v108, v107
	v_add_f32_e32 v107, 1.0, v109
	v_pk_mul_f32 v[102:103], v[102:103], v[106:107] op_sel_hi:[1,0]
	v_rcp_f32_e32 v109, v107
	v_pk_fma_f32 v[102:103], v[66:67], v[102:103], v[70:71]
	v_add_f32_dpp v111, v111, v111 row_mirror row_mask:0xf bank_mask:0xf bound_ctrl:1
	v_mul_f32_e32 v104, 0xbfb8aa3b, v102
	v_mul_f32_e32 v105, 0xbfb8aa3b, v103
	v_exp_f32_e32 v104, v104
	v_exp_f32_e32 v105, v105
	v_pk_mul_f32 v[100:101], v[100:101], v[108:109]
	v_add_f32_dpp v112, v112, v112 quad_perm:[2,3,0,1] row_mask:0xf bank_mask:0xf bound_ctrl:1
	v_add_f32_e32 v104, 1.0, v104
	v_add_f32_e32 v105, 1.0, v105
	v_rcp_f32_e32 v104, v104
	v_rcp_f32_e32 v105, v105
	v_cvt_pk_bf16_f32 v100, v100, v101
	v_add_f32_dpp v113, v113, v113 quad_perm:[2,3,0,1] row_mask:0xf bank_mask:0xf bound_ctrl:1
	v_add_f32_dpp v112, v112, v112 row_half_mirror row_mask:0xf bank_mask:0xf bound_ctrl:1
	v_pk_mul_f32 v[102:103], v[102:103], v[104:105]
	v_add_f32_dpp v113, v113, v113 row_half_mirror row_mask:0xf bank_mask:0xf bound_ctrl:1
	v_cvt_pk_bf16_f32 v101, v102, v103
	v_mov_b32_e32 v102, s23
	v_mov_b32_e32 v103, s44
	v_pk_add_f32 v[102:103], s[42:43], v[102:103]
	v_readlane_b32 s42, v124, 16
	v_readlane_b32 s23, v124, 0
	v_mov_b32_e32 v107, v103
	v_mov_b32_e32 v104, s42
	v_readlane_b32 s42, v124, 48
	v_add_f32_e32 v104, s23, v104
	v_readlane_b32 s23, v124, 32
	v_mov_b32_e32 v105, s42
	v_readlane_b32 s42, v125, 0
	v_add_f32_e32 v106, s23, v105
	v_mov_b32_e32 v105, v102
	v_pk_add_f32 v[102:103], v[104:105], v[106:107]
	s_mul_i32 s23, s27, 0x1080
	v_pk_mul_f32 v[102:103], v[102:103], s[46:47] op_sel_hi:[1,0]
	s_add_i32 s23, s23, 0
	v_fma_f32 v104, -v103, v103, v102
	v_max_f32_e32 v104, 0, v104
	v_add_f32_e32 v104, 0x3727c5ac, v104
	v_rsq_f32_e32 v104, v104
	v_pk_add_f32 v[96:97], v[96:97], v[102:103] op_sel:[0,1] neg_lo:[0,1] neg_hi:[0,1]
	v_pk_add_f32 v[98:99], v[98:99], v[102:103] op_sel:[0,1] neg_lo:[0,1] neg_hi:[0,1]
	v_readlane_b32 s27, v125, 48
	v_pk_mul_f32 v[96:97], v[96:97], v[104:105] op_sel_hi:[1,0]
	v_lshl_add_u32 v122, v110, 3, s23
	v_pk_fma_f32 v[96:97], v[64:65], v[96:97], v[68:69]
	v_readlane_b32 s23, v125, 16
	v_mul_f32_e32 v105, 0xbfb8aa3b, v96
	v_exp_f32_e32 v105, v105
	v_mul_f32_e32 v106, 0xbfb8aa3b, v97
	v_exp_f32_e32 v107, v106
	v_readlane_b32 s43, v125, 32
	v_add_f32_e32 v105, 1.0, v105
	v_rcp_f32_e32 v106, v105
	v_add_f32_e32 v105, 1.0, v107
	v_pk_mul_f32 v[98:99], v[98:99], v[104:105] op_sel_hi:[1,0]
	v_rcp_f32_e32 v107, v105
	v_mov_b32_e32 v105, s27
	v_readlane_b32 s27, v111, 16
	v_mov_b32_e32 v104, s23
	v_readlane_b32 s23, v111, 0
	v_mov_b32_e32 v108, s27
	v_readlane_b32 s27, v111, 48
	v_pk_add_f32 v[104:105], s[42:43], v[104:105]
	v_add_f32_e32 v108, s23, v108
	v_readlane_b32 s23, v111, 32
	v_mov_b32_e32 v109, s27
	v_mov_b32_e32 v111, v105
	v_add_f32_e32 v110, s23, v109
	v_mov_b32_e32 v109, v104
	v_pk_fma_f32 v[98:99], v[66:67], v[98:99], v[70:71]
	v_pk_add_f32 v[104:105], v[108:109], v[110:111]
	v_mul_f32_e32 v102, 0xbfb8aa3b, v98
	v_mul_f32_e32 v103, 0xbfb8aa3b, v99
	v_pk_mul_f32 v[104:105], v[104:105], s[46:47] op_sel_hi:[1,0]
	v_exp_f32_e32 v102, v102
	v_exp_f32_e32 v103, v103
	v_fma_f32 v108, -v105, v105, v104
	v_max_f32_e32 v108, 0, v108
	v_add_f32_e32 v108, 0x3727c5ac, v108
	v_rsq_f32_e32 v108, v108
	v_add_f32_e32 v102, 1.0, v102
	v_add_f32_e32 v103, 1.0, v103
	v_rcp_f32_e32 v102, v102
	v_rcp_f32_e32 v103, v103
	v_pk_add_f32 v[92:93], v[92:93], v[104:105] op_sel:[0,1] neg_lo:[0,1] neg_hi:[0,1]
	v_pk_mul_f32 v[96:97], v[96:97], v[106:107]
	v_pk_mul_f32 v[92:93], v[92:93], v[108:109] op_sel_hi:[1,0]
	v_pk_mul_f32 v[98:99], v[98:99], v[102:103]
	v_pk_fma_f32 v[92:93], v[64:65], v[92:93], v[68:69]
	v_pk_add_f32 v[94:95], v[94:95], v[104:105] op_sel:[0,1] neg_lo:[0,1] neg_hi:[0,1]
	v_mul_f32_e32 v102, 0xbfb8aa3b, v92
	v_exp_f32_e32 v102, v102
	v_mul_f32_e32 v103, 0xbfb8aa3b, v93
	v_exp_f32_e32 v103, v103
	v_cvt_pk_bf16_f32 v96, v96, v97
	v_add_f32_e32 v97, 1.0, v102
	v_pk_mul_f32 v[94:95], v[94:95], v[108:109] op_sel_hi:[1,0]
	v_add_f32_dpp v112, v112, v112 row_mirror row_mask:0xf bank_mask:0xf bound_ctrl:1
	v_rcp_f32_e32 v102, v97
	v_add_f32_e32 v97, 1.0, v103
	v_pk_fma_f32 v[94:95], v[66:67], v[94:95], v[70:71]
	v_add_f32_dpp v113, v113, v113 row_mirror row_mask:0xf bank_mask:0xf bound_ctrl:1
	v_rcp_f32_e32 v103, v97
	v_mul_f32_e32 v97, 0xbfb8aa3b, v94
	v_readlane_b32 s27, v112, 48
	v_exp_f32_e32 v104, v97
	v_cvt_pk_bf16_f32 v97, v98, v99
	v_readlane_b32 s23, v112, 16
	v_mov_b32_e32 v99, s27
	v_readlane_b32 s27, v113, 16
	ds_write2_b64 v122, v[100:101], v[96:97] offset1:66
	v_readlane_b32 s42, v112, 0
	v_readlane_b32 s43, v112, 32
	v_mov_b32_e32 v98, s23
	v_readlane_b32 s23, v113, 0
	v_mov_b32_e32 v100, s27
	v_readlane_b32 s27, v113, 48
	v_pk_add_f32 v[98:99], s[42:43], v[98:99]
	v_add_f32_e32 v100, s23, v100
	v_readlane_b32 s23, v113, 32
	v_mov_b32_e32 v101, s27
	v_pk_mul_f32 v[92:93], v[92:93], v[102:103]
	v_add_f32_e32 v102, s23, v101
	v_mov_b32_e32 v101, v98
	v_mov_b32_e32 v103, v99
	v_pk_add_f32 v[98:99], v[100:101], v[102:103]
	v_mul_f32_e32 v97, 0xbfb8aa3b, v95
	v_pk_mul_f32 v[98:99], v[98:99], s[46:47] op_sel_hi:[1,0]
	v_exp_f32_e32 v97, v97
	v_fma_f32 v100, -v99, v99, v98
	v_max_f32_e32 v100, 0, v100
	v_add_f32_e32 v100, 0x3727c5ac, v100
	v_rsq_f32_e32 v100, v100
	v_pk_add_f32 v[88:89], v[88:89], v[98:99] op_sel:[0,1] neg_lo:[0,1] neg_hi:[0,1]
	v_pk_add_f32 v[90:91], v[90:91], v[98:99] op_sel:[0,1] neg_lo:[0,1] neg_hi:[0,1]
	v_add_f32_e32 v96, 1.0, v104
	v_pk_mul_f32 v[88:89], v[88:89], v[100:101] op_sel_hi:[1,0]
	v_add_f32_e32 v97, 1.0, v97
	v_pk_fma_f32 v[88:89], v[64:65], v[88:89], v[68:69]
	v_rcp_f32_e32 v96, v96
	v_mul_f32_e32 v101, 0xbfb8aa3b, v88
	v_exp_f32_e32 v101, v101
	v_mul_f32_e32 v102, 0xbfb8aa3b, v89
	v_rcp_f32_e32 v97, v97
	v_exp_f32_e32 v102, v102
	v_pk_mul_f32 v[90:91], v[90:91], v[100:101] op_sel_hi:[1,0]
	v_add_f32_dpp v114, v114, v114 quad_perm:[2,3,0,1] row_mask:0xf bank_mask:0xf bound_ctrl:1
	v_pk_fma_f32 v[90:91], v[66:67], v[90:91], v[70:71]
	v_pk_mul_f32 v[94:95], v[94:95], v[96:97]
	v_mul_f32_e32 v98, 0xbfb8aa3b, v90
	v_mul_f32_e32 v99, 0xbfb8aa3b, v91
	v_exp_f32_e32 v98, v98
	v_exp_f32_e32 v99, v99
	v_add_f32_e32 v96, 1.0, v101
	v_add_f32_e32 v97, 1.0, v102
	v_add_f32_dpp v115, v115, v115 quad_perm:[2,3,0,1] row_mask:0xf bank_mask:0xf bound_ctrl:1
	v_add_f32_dpp v114, v114, v114 row_half_mirror row_mask:0xf bank_mask:0xf bound_ctrl:1
	v_rcp_f32_e32 v96, v96
	v_rcp_f32_e32 v97, v97
	v_add_f32_dpp v115, v115, v115 row_half_mirror row_mask:0xf bank_mask:0xf bound_ctrl:1
	v_add_f32_dpp v114, v114, v114 row_mirror row_mask:0xf bank_mask:0xf bound_ctrl:1
	v_add_f32_e32 v98, 1.0, v98
	v_add_f32_e32 v99, 1.0, v99
	v_add_f32_dpp v115, v115, v115 row_mirror row_mask:0xf bank_mask:0xf bound_ctrl:1
	v_rcp_f32_e32 v98, v98
	v_rcp_f32_e32 v99, v99
	v_readlane_b32 s27, v114, 48
	v_cvt_pk_bf16_f32 v92, v92, v93
	v_cvt_pk_bf16_f32 v93, v94, v95
	v_readlane_b32 s23, v114, 16
	v_mov_b32_e32 v95, s27
	v_readlane_b32 s27, v115, 16
	v_pk_mul_f32 v[88:89], v[88:89], v[96:97]
	v_readlane_b32 s42, v114, 0
	v_readlane_b32 s43, v114, 32
	v_mov_b32_e32 v94, s23
	v_readlane_b32 s23, v115, 0
	v_mov_b32_e32 v96, s27
	v_readlane_b32 s27, v115, 48
	v_pk_add_f32 v[94:95], s[42:43], v[94:95]
	v_add_f32_e32 v96, s23, v96
	v_readlane_b32 s23, v115, 32
	v_mov_b32_e32 v97, s27
	v_pk_mul_f32 v[90:91], v[90:91], v[98:99]
	v_add_f32_e32 v98, s23, v97
	v_mov_b32_e32 v97, v94
	v_mov_b32_e32 v99, v95
	v_pk_add_f32 v[94:95], v[96:97], v[98:99]
	v_cvt_pk_bf16_f32 v88, v88, v89
	v_pk_mul_f32 v[94:95], v[94:95], s[46:47] op_sel_hi:[1,0]
	v_cvt_pk_bf16_f32 v89, v90, v91
	v_fma_f32 v96, -v95, v95, v94
	v_max_f32_e32 v96, 0, v96
	v_add_f32_e32 v96, 0x3727c5ac, v96
	v_rsq_f32_e32 v96, v96
	v_pk_add_f32 v[84:85], v[84:85], v[94:95] op_sel:[0,1] neg_lo:[0,1] neg_hi:[0,1]
	v_pk_add_f32 v[86:87], v[86:87], v[94:95] op_sel:[0,1] neg_lo:[0,1] neg_hi:[0,1]
	ds_write2_b64 v122, v[92:93], v[88:89] offset0:132 offset1:198
	v_pk_mul_f32 v[84:85], v[84:85], v[96:97] op_sel_hi:[1,0]
	v_pk_mul_f32 v[86:87], v[86:87], v[96:97] op_sel_hi:[1,0]
	v_pk_fma_f32 v[84:85], v[64:65], v[84:85], v[68:69]
	v_pk_fma_f32 v[86:87], v[66:67], v[86:87], v[70:71]
	v_mul_f32_e32 v90, 0xbfb8aa3b, v84
	v_mul_f32_e32 v91, 0xbfb8aa3b, v85
	v_exp_f32_e32 v90, v90
	v_exp_f32_e32 v91, v91
	v_add_f32_dpp v116, v116, v116 quad_perm:[2,3,0,1] row_mask:0xf bank_mask:0xf bound_ctrl:1
	v_add_f32_dpp v117, v117, v117 quad_perm:[2,3,0,1] row_mask:0xf bank_mask:0xf bound_ctrl:1
	v_add_f32_e32 v88, 1.0, v90
	v_add_f32_e32 v89, 1.0, v91
	v_mul_f32_e32 v91, 0xbfb8aa3b, v87
	v_rcp_f32_e32 v88, v88
	v_rcp_f32_e32 v89, v89
	v_mul_f32_e32 v90, 0xbfb8aa3b, v86
	v_exp_f32_e32 v91, v91
	v_add_f32_dpp v116, v116, v116 row_half_mirror row_mask:0xf bank_mask:0xf bound_ctrl:1
	v_exp_f32_e32 v90, v90
	v_add_f32_dpp v117, v117, v117 row_half_mirror row_mask:0xf bank_mask:0xf bound_ctrl:1
	v_add_f32_dpp v116, v116, v116 row_mirror row_mask:0xf bank_mask:0xf bound_ctrl:1
	v_pk_mul_f32 v[84:85], v[84:85], v[88:89]
	v_add_f32_dpp v117, v117, v117 row_mirror row_mask:0xf bank_mask:0xf bound_ctrl:1
	v_readlane_b32 s27, v116, 48
	v_add_f32_e32 v89, 1.0, v91
	v_readlane_b32 s23, v116, 16
	v_mov_b32_e32 v91, s27
	v_readlane_b32 s27, v117, 16
	v_add_f32_e32 v88, 1.0, v90
	v_readlane_b32 s42, v116, 0
	v_readlane_b32 s43, v116, 32
	v_mov_b32_e32 v90, s23
	v_readlane_b32 s23, v117, 0
	v_mov_b32_e32 v92, s27
	v_readlane_b32 s27, v117, 48
	v_pk_add_f32 v[90:91], s[42:43], v[90:91]
	v_add_f32_e32 v92, s23, v92
	v_readlane_b32 s23, v117, 32
	v_mov_b32_e32 v93, s27
	v_mov_b32_e32 v95, v91
	v_add_f32_e32 v94, s23, v93
	v_mov_b32_e32 v93, v90
	v_pk_add_f32 v[90:91], v[92:93], v[94:95]
	v_rcp_f32_e32 v88, v88
	v_pk_mul_f32 v[90:91], v[90:91], s[46:47] op_sel_hi:[1,0]
	v_rcp_f32_e32 v89, v89
	v_fma_f32 v92, -v91, v91, v90
	v_max_f32_e32 v92, 0, v92
	v_add_f32_e32 v92, 0x3727c5ac, v92
	v_rsq_f32_e32 v92, v92
	v_pk_add_f32 v[80:81], v[80:81], v[90:91] op_sel:[0,1] neg_lo:[0,1] neg_hi:[0,1]
	v_cvt_pk_bf16_f32 v84, v84, v85
	v_pk_mul_f32 v[86:87], v[86:87], v[88:89]
	v_pk_mul_f32 v[80:81], v[80:81], v[92:93] op_sel_hi:[1,0]
	v_pk_add_f32 v[82:83], v[82:83], v[90:91] op_sel:[0,1] neg_lo:[0,1] neg_hi:[0,1]
	v_pk_fma_f32 v[80:81], v[64:65], v[80:81], v[68:69]
	v_pk_mul_f32 v[82:83], v[82:83], v[92:93] op_sel_hi:[1,0]
	v_mul_f32_e32 v85, 0xbfb8aa3b, v80
	v_exp_f32_e32 v88, v85
	v_mul_f32_e32 v85, 0xbfb8aa3b, v81
	v_exp_f32_e32 v89, v85
	v_pk_fma_f32 v[82:83], v[66:67], v[82:83], v[70:71]
	v_cvt_pk_bf16_f32 v85, v86, v87
	v_add_f32_e32 v86, 1.0, v88
	v_add_f32_e32 v87, 1.0, v89
	v_mul_f32_e32 v89, 0xbfb8aa3b, v83
	v_add_f32_dpp v118, v118, v118 quad_perm:[2,3,0,1] row_mask:0xf bank_mask:0xf bound_ctrl:1
	v_rcp_f32_e32 v86, v86
	v_rcp_f32_e32 v87, v87
	v_mul_f32_e32 v88, 0xbfb8aa3b, v82
	v_exp_f32_e32 v89, v89
	v_add_f32_dpp v119, v119, v119 quad_perm:[2,3,0,1] row_mask:0xf bank_mask:0xf bound_ctrl:1
	v_add_f32_dpp v118, v118, v118 row_half_mirror row_mask:0xf bank_mask:0xf bound_ctrl:1
	v_exp_f32_e32 v88, v88
	v_add_f32_dpp v119, v119, v119 row_half_mirror row_mask:0xf bank_mask:0xf bound_ctrl:1
	v_add_f32_dpp v118, v118, v118 row_mirror row_mask:0xf bank_mask:0xf bound_ctrl:1
	v_pk_mul_f32 v[80:81], v[80:81], v[86:87]
	v_add_f32_dpp v119, v119, v119 row_mirror row_mask:0xf bank_mask:0xf bound_ctrl:1
	v_readlane_b32 s27, v118, 48
	v_add_f32_e32 v87, 1.0, v89
	v_readlane_b32 s23, v118, 16
	v_mov_b32_e32 v89, s27
	v_readlane_b32 s27, v119, 16
	v_add_f32_e32 v86, 1.0, v88
	v_readlane_b32 s42, v118, 0
	v_readlane_b32 s43, v118, 32
	v_mov_b32_e32 v88, s23
	v_readlane_b32 s23, v119, 0
	v_mov_b32_e32 v90, s27
	v_readlane_b32 s27, v119, 48
	v_pk_add_f32 v[88:89], s[42:43], v[88:89]
	v_add_f32_e32 v90, s23, v90
	v_readlane_b32 s23, v119, 32
	v_mov_b32_e32 v91, s27
	v_mov_b32_e32 v93, v89
	v_add_f32_e32 v92, s23, v91
	v_mov_b32_e32 v91, v88
	v_pk_add_f32 v[88:89], v[90:91], v[92:93]
	v_rcp_f32_e32 v86, v86
	v_pk_mul_f32 v[88:89], v[88:89], s[46:47] op_sel_hi:[1,0]
	v_rcp_f32_e32 v87, v87
	v_fma_f32 v90, -v89, v89, v88
	v_max_f32_e32 v90, 0, v90
	v_add_f32_e32 v90, 0x3727c5ac, v90
	v_rsq_f32_e32 v90, v90
	v_pk_add_f32 v[76:77], v[76:77], v[88:89] op_sel:[0,1] neg_lo:[0,1] neg_hi:[0,1]
	v_cvt_pk_bf16_f32 v80, v80, v81
	v_pk_mul_f32 v[82:83], v[82:83], v[86:87]
	v_pk_mul_f32 v[76:77], v[76:77], v[90:91] op_sel_hi:[1,0]
	v_pk_add_f32 v[78:79], v[78:79], v[88:89] op_sel:[0,1] neg_lo:[0,1] neg_hi:[0,1]
	v_pk_fma_f32 v[76:77], v[64:65], v[76:77], v[68:69]
	v_add_f32_dpp v120, v120, v120 quad_perm:[2,3,0,1] row_mask:0xf bank_mask:0xf bound_ctrl:1
	v_mul_f32_e32 v81, 0xbfb8aa3b, v76
	v_exp_f32_e32 v86, v81
	v_mul_f32_e32 v81, 0xbfb8aa3b, v77
	v_exp_f32_e32 v87, v81
	v_cvt_pk_bf16_f32 v81, v82, v83
	v_add_f32_e32 v82, 1.0, v86
	v_rcp_f32_e32 v82, v82
	v_add_f32_e32 v83, 1.0, v87
	v_rcp_f32_e32 v83, v83
	v_pk_mul_f32 v[78:79], v[78:79], v[90:91] op_sel_hi:[1,0]
	v_add_f32_dpp v120, v120, v120 row_half_mirror row_mask:0xf bank_mask:0xf bound_ctrl:1
	v_pk_fma_f32 v[78:79], v[66:67], v[78:79], v[70:71]
	v_add_f32_dpp v121, v121, v121 row_mirror row_mask:0xf bank_mask:0xf bound_ctrl:1
	v_add_f32_dpp v120, v120, v120 row_mirror row_mask:0xf bank_mask:0xf bound_ctrl:1
	v_mul_f32_e32 v86, 0xbfb8aa3b, v78
	v_exp_f32_e32 v86, v86
	v_readlane_b32 s27, v120, 48
	v_add_u32_e32 v88, 0x800, v122
	v_pk_mul_f32 v[76:77], v[76:77], v[82:83]
	v_readlane_b32 s23, v120, 16
	v_mov_b32_e32 v83, s27
	v_readlane_b32 s27, v121, 16
	ds_write2_b64 v88, v[84:85], v[80:81] offset0:8 offset1:74
	v_readlane_b32 s42, v120, 0
	v_readlane_b32 s43, v120, 32
	v_mov_b32_e32 v82, s23
	v_readlane_b32 s23, v121, 0
	v_mov_b32_e32 v84, s27
	v_readlane_b32 s27, v121, 48
	v_pk_add_f32 v[82:83], s[42:43], v[82:83]
	v_add_f32_e32 v84, s23, v84
	v_readlane_b32 s23, v121, 32
	v_mov_b32_e32 v85, s27
	v_add_f32_e32 v80, 1.0, v86
	v_add_f32_e32 v86, s23, v85
	v_mov_b32_e32 v85, v82
	v_mov_b32_e32 v87, v83
	v_pk_add_f32 v[82:83], v[84:85], v[86:87]
	v_mul_f32_e32 v81, 0xbfb8aa3b, v79
	v_pk_mul_f32 v[82:83], v[82:83], s[46:47] op_sel_hi:[1,0]
	v_exp_f32_e32 v81, v81
	v_fma_f32 v84, -v83, v83, v82
	v_max_f32_e32 v84, 0, v84
	v_add_f32_e32 v84, 0x3727c5ac, v84
	v_rsq_f32_e32 v84, v84
	v_pk_add_f32 v[72:73], v[72:73], v[82:83] op_sel:[0,1] neg_lo:[0,1] neg_hi:[0,1]
	v_pk_add_f32 v[74:75], v[74:75], v[82:83] op_sel:[0,1] neg_lo:[0,1] neg_hi:[0,1]
	v_add_f32_e32 v81, 1.0, v81
	v_pk_mul_f32 v[72:73], v[72:73], v[84:85] op_sel_hi:[1,0]
	v_pk_mul_f32 v[74:75], v[74:75], v[84:85] op_sel_hi:[1,0]
	v_pk_fma_f32 v[64:65], v[64:65], v[72:73], v[68:69]
	v_pk_fma_f32 v[66:67], v[66:67], v[74:75], v[70:71]
	v_mul_f32_e32 v68, 0xbfb8aa3b, v64
	v_exp_f32_e32 v72, v68
	v_mul_f32_e32 v68, 0xbfb8aa3b, v65
	v_mul_f32_e32 v70, 0xbfb8aa3b, v66
	v_mul_f32_e32 v71, 0xbfb8aa3b, v67
	v_exp_f32_e32 v73, v68
	v_exp_f32_e32 v70, v70
	v_exp_f32_e32 v71, v71
	v_add_f32_e32 v72, 1.0, v72
	v_add_f32_e32 v73, 1.0, v73
	v_add_f32_e32 v70, 1.0, v70
	v_add_f32_e32 v71, 1.0, v71
	v_rcp_f32_e32 v80, v80
	v_rcp_f32_e32 v81, v81
	v_rcp_f32_e32 v72, v72
	v_rcp_f32_e32 v73, v73
	v_rcp_f32_e32 v70, v70
	v_rcp_f32_e32 v71, v71
	v_pk_mul_f32 v[68:69], v[78:79], v[80:81]
	v_pk_mul_f32 v[64:65], v[64:65], v[72:73]
	v_cvt_pk_bf16_f32 v74, v76, v77
	v_pk_mul_f32 v[66:67], v[66:67], v[70:71]
	v_cvt_pk_bf16_f32 v75, v68, v69
	v_cvt_pk_bf16_f32 v64, v64, v65
	v_cvt_pk_bf16_f32 v65, v66, v67
	ds_write2_b64 v88, v[74:75], v[64:65] offset0:140 offset1:206
	v_mul_u32_u24_e32 v64, 0x210, v158
	v_add3_u32 v108, 0, v148, v64
	s_waitcnt lgkmcnt(0)
	s_barrier
	ds_read_b128 v[64:67], v108
	ds_read_b128 v[68:71], v108 offset:64
	ds_read_b128 v[76:79], v108 offset:8448
	ds_read_b128 v[80:83], v108 offset:8512
	ds_read_b128 v[88:91], v108 offset:16896
	ds_read_b128 v[92:95], v108 offset:16960
	ds_read_b128 v[100:103], v108 offset:25344
	ds_read_b128 v[104:107], v108 offset:25408
	s_waitcnt lgkmcnt(7)
	v_mfma_f32_16x16x32_bf16 v[72:75], v[64:67], v[56:59], 0
	v_readlane_b32 s23, v254, 36
	v_mfma_f32_16x16x32_bf16 v[64:67], v[64:67], v[60:63], 0
	s_waitcnt lgkmcnt(5)
	v_mfma_f32_16x16x32_bf16 v[84:87], v[76:79], v[56:59], 0
	v_mfma_f32_16x16x32_bf16 v[76:79], v[76:79], v[60:63], 0
	s_waitcnt lgkmcnt(3)
	v_mfma_f32_16x16x32_bf16 v[96:99], v[88:91], v[56:59], 0
	v_mfma_f32_16x16x32_bf16 v[88:91], v[88:91], v[60:63], 0
	s_waitcnt lgkmcnt(1)
	v_mfma_f32_16x16x32_bf16 v[56:59], v[100:103], v[56:59], 0
	v_mfma_f32_16x16x32_bf16 v[60:63], v[100:103], v[60:63], 0
	v_mfma_f32_16x16x32_bf16 v[72:75], v[68:71], v[48:51], v[72:75]
	v_mfma_f32_16x16x32_bf16 v[64:67], v[68:71], v[52:55], v[64:67]
	v_mfma_f32_16x16x32_bf16 v[68:71], v[80:83], v[48:51], v[84:87]
	v_mfma_f32_16x16x32_bf16 v[76:79], v[80:83], v[52:55], v[76:79]
	v_mfma_f32_16x16x32_bf16 v[80:83], v[92:95], v[48:51], v[96:99]
	v_mfma_f32_16x16x32_bf16 v[84:87], v[92:95], v[52:55], v[88:91]
	s_waitcnt lgkmcnt(0)
	v_mfma_f32_16x16x32_bf16 v[48:51], v[104:107], v[48:51], v[56:59]
	v_mfma_f32_16x16x32_bf16 v[52:55], v[104:107], v[52:55], v[60:63]
	s_nop 1
	ds_read_b128 v[56:59], v108 offset:128
	ds_read_b128 v[60:63], v108 offset:192
	s_waitcnt lgkmcnt(1)
	v_mfma_f32_16x16x32_bf16 v[72:75], v[56:59], v[40:43], v[72:75]
	v_mfma_f32_16x16x32_bf16 v[56:59], v[56:59], v[44:47], v[64:67]
	s_nop 2
	ds_read_b128 v[64:67], v108 offset:8576
	ds_read_b128 v[88:91], v108 offset:8640
	s_waitcnt lgkmcnt(1)
	v_mfma_f32_16x16x32_bf16 v[68:71], v[64:67], v[40:43], v[68:71]
	v_mfma_f32_16x16x32_bf16 v[64:67], v[64:67], v[44:47], v[76:79]
	s_nop 2
	ds_read_b128 v[76:79], v108 offset:17024
	ds_read_b128 v[92:95], v108 offset:17088
	s_waitcnt lgkmcnt(1)
	v_mfma_f32_16x16x32_bf16 v[80:83], v[76:79], v[40:43], v[80:83]
	v_mfma_f32_16x16x32_bf16 v[76:79], v[76:79], v[44:47], v[84:87]
	s_nop 2
	ds_read_b128 v[84:87], v108 offset:25472
	ds_read_b128 v[96:99], v108 offset:25536
	s_waitcnt lgkmcnt(1)
	v_mfma_f32_16x16x32_bf16 v[40:43], v[84:87], v[40:43], v[48:51]
	v_mfma_f32_16x16x32_bf16 v[44:47], v[84:87], v[44:47], v[52:55]
	v_mfma_f32_16x16x32_bf16 v[48:51], v[60:63], v[32:35], v[72:75]
	v_mfma_f32_16x16x32_bf16 v[52:55], v[60:63], v[36:39], v[56:59]
	v_mfma_f32_16x16x32_bf16 v[56:59], v[88:91], v[32:35], v[68:71]
	v_mfma_f32_16x16x32_bf16 v[60:63], v[88:91], v[36:39], v[64:67]
	v_mfma_f32_16x16x32_bf16 v[64:67], v[92:95], v[32:35], v[80:83]
	v_mfma_f32_16x16x32_bf16 v[68:71], v[92:95], v[36:39], v[76:79]
	s_waitcnt lgkmcnt(0)
	v_mfma_f32_16x16x32_bf16 v[32:35], v[96:99], v[32:35], v[40:43]
	v_mfma_f32_16x16x32_bf16 v[36:39], v[96:99], v[36:39], v[44:47]
	s_nop 1
	ds_read_b128 v[40:43], v108 offset:256
	ds_read_b128 v[44:47], v108 offset:320
	s_waitcnt lgkmcnt(1)
	v_mfma_f32_16x16x32_bf16 v[48:51], v[40:43], v[24:27], v[48:51]
	v_mfma_f32_16x16x32_bf16 v[40:43], v[40:43], v[28:31], v[52:55]
	s_nop 2
	ds_read_b128 v[52:55], v108 offset:8704
	ds_read_b128 v[72:75], v108 offset:8768
	s_waitcnt lgkmcnt(1)
	v_mfma_f32_16x16x32_bf16 v[56:59], v[52:55], v[24:27], v[56:59]
	v_mfma_f32_16x16x32_bf16 v[52:55], v[52:55], v[28:31], v[60:63]
	s_nop 2
	ds_read_b128 v[60:63], v108 offset:17152
	ds_read_b128 v[76:79], v108 offset:17216
	s_waitcnt lgkmcnt(1)
	v_mfma_f32_16x16x32_bf16 v[64:67], v[60:63], v[24:27], v[64:67]
	v_mfma_f32_16x16x32_bf16 v[60:63], v[60:63], v[28:31], v[68:71]
	s_nop 2
	ds_read_b128 v[68:71], v108 offset:25600
	ds_read_b128 v[80:83], v108 offset:25664
	s_waitcnt lgkmcnt(1)
	v_mfma_f32_16x16x32_bf16 v[24:27], v[68:71], v[24:27], v[32:35]
	v_mfma_f32_16x16x32_bf16 v[28:31], v[68:71], v[28:31], v[36:39]
	v_mfma_f32_16x16x32_bf16 v[32:35], v[44:47], v[16:19], v[48:51]
	v_mfma_f32_16x16x32_bf16 v[36:39], v[44:47], v[20:23], v[40:43]
	v_mfma_f32_16x16x32_bf16 v[40:43], v[72:75], v[16:19], v[56:59]
	v_mfma_f32_16x16x32_bf16 v[44:47], v[72:75], v[20:23], v[52:55]
	v_mfma_f32_16x16x32_bf16 v[48:51], v[76:79], v[16:19], v[64:67]
	v_mfma_f32_16x16x32_bf16 v[52:55], v[76:79], v[20:23], v[60:63]
	s_waitcnt lgkmcnt(0)
	v_mfma_f32_16x16x32_bf16 v[16:19], v[80:83], v[16:19], v[24:27]
	v_mfma_f32_16x16x32_bf16 v[20:23], v[80:83], v[20:23], v[28:31]
	s_nop 1
	ds_read_b128 v[24:27], v108 offset:384
	ds_read_b128 v[28:31], v108 offset:448
	s_waitcnt lgkmcnt(1)
	v_mfma_f32_16x16x32_bf16 v[32:35], v[24:27], v[8:11], v[32:35]
	v_mfma_f32_16x16x32_bf16 v[24:27], v[24:27], v[12:15], v[36:39]
	s_nop 2
	ds_read_b128 v[36:39], v108 offset:8832
	ds_read_b128 v[56:59], v108 offset:8896
	s_waitcnt lgkmcnt(1)
	v_mfma_f32_16x16x32_bf16 v[40:43], v[36:39], v[8:11], v[40:43]
	v_mfma_f32_16x16x32_bf16 v[36:39], v[36:39], v[12:15], v[44:47]
	s_nop 2
	ds_read_b128 v[44:47], v108 offset:17280
	ds_read_b128 v[60:63], v108 offset:17344
	s_waitcnt lgkmcnt(1)
	v_mfma_f32_16x16x32_bf16 v[48:51], v[44:47], v[8:11], v[48:51]
	v_mfma_f32_16x16x32_bf16 v[44:47], v[44:47], v[12:15], v[52:55]
	s_nop 2
	ds_read_b128 v[52:55], v108 offset:25728
	ds_read_b128 v[64:67], v108 offset:25792
	s_waitcnt lgkmcnt(1)
	v_mfma_f32_16x16x32_bf16 v[68:71], v[52:55], v[8:11], v[16:19]
	v_mfma_f32_16x16x32_bf16 v[32:35], v[28:31], v[4:7], v[32:35]
	v_mfma_f32_16x16x32_bf16 v[16:19], v[28:31], v[0:3], v[24:27]
	v_or_b32_e32 v28, s26, v158
	v_lshlrev_b32_e32 v29, 7, v156
	v_and_b32_e32 v29, 0x1800, v29
	v_lshlrev_b32_e32 v28, 1, v28
	v_add3_u32 v30, s23, v28, v29
	v_mfma_f32_16x16x32_bf16 v[52:55], v[52:55], v[12:15], v[20:23]
	v_readlane_b32 s26, v254, 37
	v_mfma_f32_16x16x32_bf16 v[24:27], v[56:59], v[4:7], v[40:43]
	v_mfma_f32_16x16x32_bf16 v[12:15], v[56:59], v[0:3], v[36:39]
	ds_read_u16 v31, v30
	s_nop 1
	ds_read_u16 v36, v30 offset:512
	ds_read_u16 v37, v30 offset:1024
	ds_read_u16 v38, v30 offset:1536
	ds_read_u16 v39, v30 offset:8192
	ds_read_u16 v40, v30 offset:8704
	ds_read_u16 v41, v30 offset:9216
	ds_read_u16 v42, v30 offset:9728
	s_waitcnt lgkmcnt(7)
	v_lshlrev_b32_e32 v31, 16, v31
	v_mul_f32_e32 v43, 0xbfb8aa3b, v31
	v_exp_f32_e32 v43, v43
	s_waitcnt lgkmcnt(6)
	v_lshlrev_b32_e32 v36, 16, v36
	v_mfma_f32_16x16x32_bf16 v[8:11], v[60:63], v[0:3], v[44:47]
	s_waitcnt lgkmcnt(5)
	v_lshlrev_b32_e32 v37, 16, v37
	v_add_f32_e32 v43, 1.0, v43
	v_rcp_f32_e32 v43, v43
	v_mul_f32_e32 v44, 0xbfb8aa3b, v36
	v_exp_f32_e32 v44, v44
	v_mfma_f32_16x16x32_bf16 v[20:23], v[60:63], v[4:7], v[48:51]
	v_mul_f32_e32 v31, v43, v31
	v_mul_f32_e32 v31, v32, v31
	v_add_f32_e32 v32, 1.0, v44
	v_rcp_f32_e32 v32, v32
	v_mul_f32_e32 v43, 0xbfb8aa3b, v37
	v_exp_f32_e32 v43, v43
	v_cvt_pk_bf16_f32 v31, v31, s0
	ds_write_b16 v30, v31
	v_mul_f32_e32 v31, v32, v36
	v_mul_f32_e32 v31, v33, v31
	s_waitcnt lgkmcnt(5)
	v_lshlrev_b32_e32 v33, 16, v38
	v_add_f32_e32 v32, 1.0, v43
	v_mul_f32_e32 v36, 0xbfb8aa3b, v33
	v_rcp_f32_e32 v32, v32
	v_exp_f32_e32 v36, v36
	v_cvt_pk_bf16_f32 v31, v31, s0
	ds_write_b16 v30, v31 offset:512
	v_mul_f32_e32 v31, v32, v37
	v_add_f32_e32 v32, 1.0, v36
	v_rcp_f32_e32 v32, v32
	v_mul_f32_e32 v31, v34, v31
	v_cvt_pk_bf16_f32 v31, v31, s0
	ds_write_b16 v30, v31 offset:1024
	v_mul_f32_e32 v31, v32, v33
	s_waitcnt lgkmcnt(6)
	v_lshlrev_b32_e32 v32, 16, v39
	v_mul_f32_e32 v33, 0xbfb8aa3b, v32
	v_exp_f32_e32 v33, v33
	v_mul_f32_e32 v31, v35, v31
	v_cvt_pk_bf16_f32 v31, v31, s0
	ds_write_b16 v30, v31 offset:1536
	v_add_f32_e32 v31, 1.0, v33
	s_waitcnt lgkmcnt(6)
	v_lshlrev_b32_e32 v33, 16, v40
	v_rcp_f32_e32 v31, v31
	v_mul_f32_e32 v34, 0xbfb8aa3b, v33
	v_exp_f32_e32 v34, v34
	v_mfma_f32_16x16x32_bf16 v[4:7], v[64:67], v[4:7], v[68:71]
	v_mul_f32_e32 v31, v31, v32
	v_mul_f32_e32 v24, v24, v31
	v_add_f32_e32 v31, 1.0, v34
	s_waitcnt lgkmcnt(5)
	v_lshlrev_b32_e32 v32, 16, v41
	v_rcp_f32_e32 v31, v31
	v_mul_f32_e32 v34, 0xbfb8aa3b, v32
	v_exp_f32_e32 v34, v34
	v_cvt_pk_bf16_f32 v24, v24, s0
	ds_write_b16 v30, v24 offset:8192
	v_mul_f32_e32 v24, v31, v33
	s_waitcnt lgkmcnt(5)
	v_lshlrev_b32_e32 v31, 16, v42
	v_mul_f32_e32 v24, v25, v24
	v_add_f32_e32 v25, 1.0, v34
	v_mul_f32_e32 v33, 0xbfb8aa3b, v31
	v_rcp_f32_e32 v25, v25
	v_exp_f32_e32 v33, v33
	v_cvt_pk_bf16_f32 v24, v24, s0
	ds_write_b16 v30, v24 offset:8704
	v_mul_f32_e32 v24, v25, v32
	v_add_f32_e32 v25, 1.0, v33
	v_rcp_f32_e32 v25, v25
	v_mul_f32_e32 v24, v26, v24
	v_cvt_pk_bf16_f32 v24, v24, s0
	ds_write_b16 v30, v24 offset:9216
	v_mul_f32_e32 v24, v25, v31
	ds_read_u16 v25, v30 offset:16384
	ds_read_u16 v26, v30 offset:16896
	ds_read_u16 v31, v30 offset:17408
	ds_read_u16 v32, v30 offset:17920
	ds_read_u16 v33, v30 offset:24576
	ds_read_u16 v34, v30 offset:25088
	ds_read_u16 v35, v30 offset:25600
	ds_read_u16 v36, v30 offset:26112
	s_waitcnt lgkmcnt(7)
	v_lshlrev_b32_e32 v25, 16, v25
	v_mul_f32_e32 v37, 0xbfb8aa3b, v25
	v_exp_f32_e32 v37, v37
	v_mul_f32_e32 v24, v27, v24
	v_cvt_pk_bf16_f32 v24, v24, s0
	ds_write_b16 v30, v24 offset:9728
	v_add_f32_e32 v24, 1.0, v37
	s_waitcnt lgkmcnt(7)
	v_lshlrev_b32_e32 v26, 16, v26
	v_rcp_f32_e32 v24, v24
	v_mul_f32_e32 v27, 0xbfb8aa3b, v26
	v_exp_f32_e32 v27, v27
	v_mfma_f32_16x16x32_bf16 v[0:3], v[64:67], v[0:3], v[52:55]
	v_mul_f32_e32 v24, v24, v25
	v_mul_f32_e32 v20, v20, v24
	v_add_f32_e32 v24, 1.0, v27
	s_waitcnt lgkmcnt(6)
	v_lshlrev_b32_e32 v25, 16, v31
	v_rcp_f32_e32 v24, v24
	v_mul_f32_e32 v27, 0xbfb8aa3b, v25
	v_exp_f32_e32 v27, v27
	v_cvt_pk_bf16_f32 v20, v20, s0
	ds_write_b16 v30, v20 offset:16384
	v_mul_f32_e32 v20, v24, v26
	s_waitcnt lgkmcnt(6)
	v_lshlrev_b32_e32 v24, 16, v32
	v_mul_f32_e32 v20, v21, v20
	v_add_f32_e32 v21, 1.0, v27
	v_mul_f32_e32 v26, 0xbfb8aa3b, v24
	v_rcp_f32_e32 v21, v21
	v_exp_f32_e32 v26, v26
	v_cvt_pk_bf16_f32 v20, v20, s0
	ds_write_b16 v30, v20 offset:16896
	v_mul_f32_e32 v20, v21, v25
	v_add_f32_e32 v21, 1.0, v26
	v_rcp_f32_e32 v21, v21
	v_mul_f32_e32 v20, v22, v20
	v_cvt_pk_bf16_f32 v20, v20, s0
	ds_write_b16 v30, v20 offset:17408
	v_mul_f32_e32 v20, v21, v24
	s_waitcnt lgkmcnt(7)
	v_lshlrev_b32_e32 v21, 16, v33
	v_mul_f32_e32 v22, 0xbfb8aa3b, v21
	v_exp_f32_e32 v22, v22
	v_mul_f32_e32 v20, v23, v20
	v_cvt_pk_bf16_f32 v20, v20, s0
	ds_write_b16 v30, v20 offset:17920
	v_add_f32_e32 v20, 1.0, v22
	s_waitcnt lgkmcnt(7)
	v_lshlrev_b32_e32 v22, 16, v34
	v_rcp_f32_e32 v20, v20
	v_mul_f32_e32 v23, 0xbfb8aa3b, v22
	v_exp_f32_e32 v23, v23
	v_mul_f32_e32 v20, v20, v21
	v_mul_f32_e32 v4, v4, v20
	v_add_f32_e32 v20, 1.0, v23
	s_waitcnt lgkmcnt(6)
	v_lshlrev_b32_e32 v21, 16, v35
	v_rcp_f32_e32 v20, v20
	v_mul_f32_e32 v23, 0xbfb8aa3b, v21
	v_exp_f32_e32 v23, v23
	v_cvt_pk_bf16_f32 v4, v4, s0
	ds_write_b16 v30, v4 offset:24576
	v_mul_f32_e32 v4, v20, v22
	s_waitcnt lgkmcnt(6)
	v_lshlrev_b32_e32 v20, 16, v36
	v_mul_f32_e32 v4, v5, v4
	v_add_f32_e32 v5, 1.0, v23
	v_mul_f32_e32 v22, 0xbfb8aa3b, v20
	v_rcp_f32_e32 v5, v5
	v_exp_f32_e32 v22, v22
	v_cvt_pk_bf16_f32 v4, v4, s0
	ds_write_b16 v30, v4 offset:25088
	v_mul_f32_e32 v4, v5, v21
	v_add_f32_e32 v5, 1.0, v22
	v_rcp_f32_e32 v5, v5
	v_mul_f32_e32 v4, v6, v4
	v_cvt_pk_bf16_f32 v4, v4, s0
	ds_write_b16 v30, v4 offset:25600
	v_mul_f32_e32 v4, v5, v20
	v_add3_u32 v5, s26, v28, v29
	ds_read_u16 v6, v5
	ds_read_u16 v20, v5 offset:512
	ds_read_u16 v21, v5 offset:1024
	ds_read_u16 v22, v5 offset:1536
	ds_read_u16 v23, v5 offset:8192
	ds_read_u16 v24, v5 offset:8704
	ds_read_u16 v25, v5 offset:9216
	ds_read_u16 v26, v5 offset:9728
	s_waitcnt lgkmcnt(7)
	v_lshlrev_b32_e32 v6, 16, v6
	v_mul_f32_e32 v27, 0xbfb8aa3b, v6
	v_exp_f32_e32 v27, v27
	v_mul_f32_e32 v4, v7, v4
	v_cvt_pk_bf16_f32 v4, v4, s0
	ds_write_b16 v30, v4 offset:26112
	v_add_f32_e32 v4, 1.0, v27
	s_waitcnt lgkmcnt(7)
	v_lshlrev_b32_e32 v7, 16, v20
	v_rcp_f32_e32 v4, v4
	v_mul_f32_e32 v20, 0xbfb8aa3b, v7
	v_exp_f32_e32 v20, v20
	v_readlane_b32 s26, v255, 9
	v_mul_f32_e32 v4, v4, v6
	v_mul_f32_e32 v4, v16, v4
	v_add_f32_e32 v6, 1.0, v20
	s_waitcnt lgkmcnt(6)
	v_lshlrev_b32_e32 v16, 16, v21
	v_rcp_f32_e32 v6, v6
	v_mul_f32_e32 v20, 0xbfb8aa3b, v16
	v_exp_f32_e32 v20, v20
	v_cvt_pk_bf16_f32 v4, v4, s0
	ds_write_b16 v5, v4
	v_mul_f32_e32 v4, v6, v7
	s_waitcnt lgkmcnt(6)
	v_lshlrev_b32_e32 v7, 16, v22
	v_mul_f32_e32 v4, v17, v4
	v_add_f32_e32 v6, 1.0, v20
	v_mul_f32_e32 v17, 0xbfb8aa3b, v7
	v_rcp_f32_e32 v6, v6
	v_exp_f32_e32 v17, v17
	v_cvt_pk_bf16_f32 v4, v4, s0
	ds_write_b16 v5, v4 offset:512
	v_mul_f32_e32 v4, v6, v16
	v_add_f32_e32 v6, 1.0, v17
	v_rcp_f32_e32 v6, v6
	v_mul_f32_e32 v4, v18, v4
	v_cvt_pk_bf16_f32 v4, v4, s0
	ds_write_b16 v5, v4 offset:1024
	v_mul_f32_e32 v4, v6, v7
	s_waitcnt lgkmcnt(7)
	v_lshlrev_b32_e32 v6, 16, v23
	v_mul_f32_e32 v7, 0xbfb8aa3b, v6
	v_exp_f32_e32 v7, v7
	v_mul_f32_e32 v4, v19, v4
	v_cvt_pk_bf16_f32 v4, v4, s0
	ds_write_b16 v5, v4 offset:1536
	v_add_f32_e32 v4, 1.0, v7
	s_waitcnt lgkmcnt(7)
	v_lshlrev_b32_e32 v7, 16, v24
	v_rcp_f32_e32 v4, v4
	v_mul_f32_e32 v16, 0xbfb8aa3b, v7
	v_exp_f32_e32 v16, v16
	v_readlane_b32 s27, v255, 10
	v_mul_f32_e32 v4, v4, v6
	v_mul_f32_e32 v4, v12, v4
	v_add_f32_e32 v6, 1.0, v16
	s_waitcnt lgkmcnt(6)
	v_lshlrev_b32_e32 v12, 16, v25
	v_rcp_f32_e32 v6, v6
	v_mul_f32_e32 v16, 0xbfb8aa3b, v12
	v_exp_f32_e32 v16, v16
	v_cvt_pk_bf16_f32 v4, v4, s0
	ds_write_b16 v5, v4 offset:8192
	v_mul_f32_e32 v4, v6, v7
	s_waitcnt lgkmcnt(6)
	v_lshlrev_b32_e32 v7, 16, v26
	v_mul_f32_e32 v4, v13, v4
	v_add_f32_e32 v6, 1.0, v16
	v_mul_f32_e32 v13, 0xbfb8aa3b, v7
	v_rcp_f32_e32 v6, v6
	v_exp_f32_e32 v13, v13
	v_cvt_pk_bf16_f32 v4, v4, s0
	ds_write_b16 v5, v4 offset:8704
	v_mul_f32_e32 v4, v6, v12
	v_add_f32_e32 v6, 1.0, v13
	v_rcp_f32_e32 v6, v6
	v_mul_f32_e32 v4, v14, v4
	v_cvt_pk_bf16_f32 v4, v4, s0
	ds_write_b16 v5, v4 offset:9216
	v_mul_f32_e32 v4, v6, v7
	ds_read_u16 v6, v5 offset:16384
	ds_read_u16 v7, v5 offset:16896
	ds_read_u16 v12, v5 offset:17408
	ds_read_u16 v13, v5 offset:17920
	ds_read_u16 v14, v5 offset:24576
	ds_read_u16 v16, v5 offset:25088
	ds_read_u16 v17, v5 offset:25600
	ds_read_u16 v18, v5 offset:26112
	s_waitcnt lgkmcnt(7)
	v_lshlrev_b32_e32 v6, 16, v6
	v_mul_f32_e32 v19, 0xbfb8aa3b, v6
	v_exp_f32_e32 v19, v19
	v_mul_f32_e32 v4, v15, v4
	v_cvt_pk_bf16_f32 v4, v4, s0
	ds_write_b16 v5, v4 offset:9728
	v_add_f32_e32 v4, 1.0, v19
	s_waitcnt lgkmcnt(7)
	v_lshlrev_b32_e32 v7, 16, v7
	v_rcp_f32_e32 v4, v4
	v_mul_f32_e32 v15, 0xbfb8aa3b, v7
	v_exp_f32_e32 v15, v15
	v_mul_f32_e32 v4, v4, v6
	v_mul_f32_e32 v4, v8, v4
	v_add_f32_e32 v6, 1.0, v15
	s_waitcnt lgkmcnt(6)
	v_lshlrev_b32_e32 v8, 16, v12
	v_rcp_f32_e32 v6, v6
	v_mul_f32_e32 v12, 0xbfb8aa3b, v8
	v_exp_f32_e32 v12, v12
	v_cvt_pk_bf16_f32 v4, v4, s0
	ds_write_b16 v5, v4 offset:16384
	v_mul_f32_e32 v4, v6, v7
	s_waitcnt lgkmcnt(6)
	v_lshlrev_b32_e32 v7, 16, v13
	v_mul_f32_e32 v4, v9, v4
	v_add_f32_e32 v6, 1.0, v12
	v_mul_f32_e32 v9, 0xbfb8aa3b, v7
	v_rcp_f32_e32 v6, v6
	v_exp_f32_e32 v9, v9
	v_cvt_pk_bf16_f32 v4, v4, s0
	ds_write_b16 v5, v4 offset:16896
	v_mul_f32_e32 v4, v6, v8
	v_add_f32_e32 v6, 1.0, v9
	v_rcp_f32_e32 v6, v6
	v_mul_f32_e32 v4, v10, v4
	v_cvt_pk_bf16_f32 v4, v4, s0
	ds_write_b16 v5, v4 offset:17408
	v_mul_f32_e32 v4, v6, v7
	s_waitcnt lgkmcnt(7)
	v_lshlrev_b32_e32 v6, 16, v14
	v_mul_f32_e32 v7, 0xbfb8aa3b, v6
	v_exp_f32_e32 v7, v7
	v_mul_f32_e32 v4, v11, v4
	v_cvt_pk_bf16_f32 v4, v4, s0
	ds_write_b16 v5, v4 offset:17920
	v_add_f32_e32 v4, 1.0, v7
	s_waitcnt lgkmcnt(7)
	v_lshlrev_b32_e32 v7, 16, v16
	v_rcp_f32_e32 v4, v4
	v_mul_f32_e32 v8, 0xbfb8aa3b, v7
	v_exp_f32_e32 v8, v8
	v_mul_f32_e32 v4, v4, v6
	v_mul_f32_e32 v0, v0, v4
	v_add_f32_e32 v4, 1.0, v8
	s_waitcnt lgkmcnt(6)
	v_lshlrev_b32_e32 v6, 16, v17
	v_rcp_f32_e32 v4, v4
	v_mul_f32_e32 v8, 0xbfb8aa3b, v6
	v_exp_f32_e32 v8, v8
	v_cvt_pk_bf16_f32 v0, v0, s0
	ds_write_b16 v5, v0 offset:24576
	v_mul_f32_e32 v0, v4, v7
	s_waitcnt lgkmcnt(6)
	v_lshlrev_b32_e32 v4, 16, v18
	v_mul_f32_e32 v0, v1, v0
	v_add_f32_e32 v1, 1.0, v8
	v_mul_f32_e32 v7, 0xbfb8aa3b, v4
	v_rcp_f32_e32 v1, v1
	v_exp_f32_e32 v7, v7
	v_cvt_pk_bf16_f32 v0, v0, s0
	ds_write_b16 v5, v0 offset:25088
	v_mul_f32_e32 v0, v1, v6
	v_add_f32_e32 v1, 1.0, v7
	v_rcp_f32_e32 v1, v1
	v_mul_f32_e32 v0, v2, v0
	v_cvt_pk_bf16_f32 v0, v0, s0
	ds_write_b16 v5, v0 offset:25600
	v_mul_f32_e32 v0, v1, v4
	v_mul_f32_e32 v0, v3, v0
	v_cvt_pk_bf16_f32 v0, v0, s0
	ds_write_b16 v5, v0 offset:26112
	v_ashrrev_i32_e32 v0, 31, v156
	v_lshrrev_b32_e32 v0, 27, v0
	v_add_u32_e32 v0, v156, v0
	v_ashrrev_i32_e32 v8, 5, v0
	v_and_b32_e32 v0, 0xffffffe0, v0
	v_sub_u32_e32 v2, v156, v0
	v_lshlrev_b32_e32 v0, 3, v2
	v_add_u32_e32 v6, s65, v8
	v_ashrrev_i32_e32 v1, 31, v0
	v_ashrrev_i32_e32 v7, 31, v6
	v_lshl_add_u64 v[4:5], v[0:1], 1, s[26:27]
	v_lshl_add_u32 v9, v2, 4, s23
	v_lshlrev_b64 v[6:7], 11, v[6:7]
	v_lshl_add_u32 v0, v8, 9, v9
	v_lshl_add_u64 v[6:7], v[4:5], 0, v[6:7]
	s_waitcnt lgkmcnt(0)
	s_barrier
	ds_read_b128 v[0:3], v0
	s_waitcnt lgkmcnt(0)
	global_store_dwordx4 v[6:7], v[0:3], off sc1
	s_nop 1
	v_add_u32_e32 v6, 16, v8
	v_lshl_add_u32 v0, v6, 9, v9
	v_add_u32_e32 v6, s65, v6
	v_ashrrev_i32_e32 v7, 31, v6
	v_lshlrev_b64 v[6:7], 11, v[6:7]
	v_lshl_add_u64 v[6:7], v[4:5], 0, v[6:7]
	ds_read_b128 v[0:3], v0
	s_waitcnt lgkmcnt(0)
	global_store_dwordx4 v[6:7], v[0:3], off sc1
	s_nop 1
	v_add_u32_e32 v6, 32, v8
	v_lshl_add_u32 v0, v6, 9, v9
	v_add_u32_e32 v6, s65, v6
	v_ashrrev_i32_e32 v7, 31, v6
	v_lshlrev_b64 v[6:7], 11, v[6:7]
	v_lshl_add_u64 v[6:7], v[4:5], 0, v[6:7]
	ds_read_b128 v[0:3], v0
	s_waitcnt lgkmcnt(0)
	global_store_dwordx4 v[6:7], v[0:3], off sc1
	s_nop 1
	v_add_u32_e32 v6, 48, v8
	v_lshl_add_u32 v0, v6, 9, v9
	v_add_u32_e32 v6, s65, v6
	v_ashrrev_i32_e32 v7, 31, v6
	v_lshlrev_b64 v[6:7], 11, v[6:7]
	ds_read_b128 v[0:3], v0
	v_lshl_add_u64 v[4:5], v[4:5], 0, v[6:7]
	s_waitcnt lgkmcnt(0)
	global_store_dwordx4 v[4:5], v[0:3], off sc1
	s_nop 1
	s_mov_b64 s[26:27], 0
	s_barrier
